# GEMM K-loops: compute-segment edges trimmed - s_setprio 1 hoisted above the opening barrier, satisfied lgkmcnt(0) and the no-op mid-burst prio flip dropped, closing barrier ahead of s_setprio 0
# baseline (speedup 1.0000x reference)
; #define PG8_STAGE(bufoff, gbase, voff) do { _Pragma("unroll") for (int _i = 0; _i < 2; ++_i) \
;         __builtin_amdgcn_global_load_lds((const unsigned*)((const char*)(gbase) + (voff)[_i]), (PG8_LAS unsigned*)(lds + (bufoff) + ldsw + _i * 8192), 16, 0, 0); } while (0)
; #define PG8_LDA(dst, b, h) do { _Pragma("unroll") for (int m = 0; m < 4; ++m) _Pragma("unroll") for (int k = 0; k < 2; ++k) dst[m][k] = *(const PG8_LAS bf16x8*)(lds + PG8_SA(b, h) + aoff + m * 2048 + k * 1024); } while (0)
; #define PG8_LDB(dst, b, h) do { _Pragma("unroll") for (int n = 0; n < 2; ++n) _Pragma("unroll") for (int k = 0; k < 2; ++k) dst[n][k] = *(const PG8_LAS bf16x8*)(lds + PG8_SB(b, h) + boff + n * 2048 + k * 1024); } while (0)
; #define PG8_WAIT_V(n) asm volatile("s_waitcnt vmcnt(" #n ")" ::: "memory")
; #define PG8_WAIT_L(n) asm volatile("s_waitcnt lgkmcnt(" #n ")" ::: "memory")
; #define PG8_BAR __builtin_amdgcn_s_barrier()
; #define PG8_SCHED __builtin_amdgcn_sched_barrier(0)
; template <class Epi, class Sched, bool ALIGN_EPI = false, bool SP2 = false>
; __device__ __forceinline__ void gemm_phase(PG8_LAS unsigned char* lds, const Gemm g, const Sched& S, const Epi& E) {
;     ...
;             const char* a1 = cA + (g.gstrA ? (size_t)(t >> 2) * g.gstrA + (size_t)(t & 3) * kstep : (size_t)t * kstep) + kstep;
;             const char* a2 = last ? nA : cA + (g.gstrA ? (size_t)((t + 2) >> 2) * g.gstrA + (size_t)((t + 2) & 3) * kstep : (size_t)(t + 2) * kstep); const char* b2 = last ? nB : cB + (size_t)(t + 2) * kstep;
;             const char* a3 = a2 + kstep; const char* b3 = b2 + kstep;
;             if (last && has_next) S.a_ready(nxt);
;             if constexpr (Epi::HAS_PREFETCH) { if (t == nt - 4) E.prefetch(cur, tid, wid); }
;             if constexpr (SP2) {
;             PG8_LDB(B0, 0, 0); PG8_LDB(B1, 0, 1); PG8_SCHED; PG8_LDA(At, 0, 0); PG8_STAGE(PG8_SA(1, 1), a1 + hstepA, voffA);
;             PG8_WAIT_V(8); PG8_WAIT_L(0); PG8_BAR; PG8_MMA(0, 0, At, B0); PG8_MMA(0, 1, At, B1); PG8_BAR; PG8_SCHED;
;             PG8_LDA(At, 0, 1); PG8_STAGE(PG8_SB(0, 0), b2, voffB); PG8_STAGE(PG8_SB(0, 1), b2 + hstep, voffB); PG8_STAGE(PG8_SA(0, 0), a2, voffA);
;             PG8_WAIT_V(8); PG8_WAIT_L(0); PG8_BAR; PG8_MMA(1, 0, At, B0); PG8_MMA(1, 1, At, B1); PG8_BAR; PG8_SCHED;
.LBB0_53:
	s_add_u32 s14, s82, 0xfffc0080
	s_addc_u32 s15, s83, -1
	s_add_i32 s38, 0, 0x10000
	s_cmp_eq_u32 s52, 12
	s_cselect_b32 s15, s18, s15
	s_cselect_b32 s14, s24, s14
	s_cselect_b32 s41, s26, s36
	s_cselect_b32 s40, s30, s34
	s_add_i32 s56, 0, 0x14000
	v_add_u32_e32 v44, s38, v174
	v_add_u32_e32 v157, s56, v174
	ds_read_b128 v[24:27], v44
	ds_read_b128 v[28:31], v44 offset:1024
	ds_read_b128 v[40:43], v44 offset:2048
	ds_read_b128 v[44:47], v44 offset:3072
	ds_read_b128 v[186:189], v157
	ds_read_b128 v[190:193], v157 offset:1024
	ds_read_b128 v[194:197], v157 offset:2048
	ds_read_b128 v[198:201], v157 offset:3072
	v_lshl_add_u64 v[170:171], s[82:83], 0, v[152:153]
	s_add_i32 m0, s3, 0xc000
	ds_read_b128 v[202:205], v184
	ds_read_b128 v[206:209], v184 offset:1024
	ds_read_b128 v[214:217], v184 offset:2048
	ds_read_b128 v[218:221], v184 offset:3072
	ds_read_b128 v[222:225], v184 offset:4096
	ds_read_b128 v[240:243], v184 offset:5120
	ds_read_b128 v[244:247], v184 offset:6144
	ds_read_b128 v[248:251], v184 offset:7168
	global_load_lds_dwordx4 v[170:171], off
	v_lshl_add_u64 v[170:171], s[82:83], 0, v[154:155]
	s_add_i32 m0, s3, 0xe000
	s_nop 0
	global_load_lds_dwordx4 v[170:171], off
	s_waitcnt vmcnt(8)
	s_waitcnt lgkmcnt(0)
	s_setprio 1
	s_barrier
	v_mfma_f32_16x16x32_bf16 v[140:143], v[24:27], v[202:205], v[140:143]
	v_mfma_f32_16x16x32_bf16 v[136:139], v[40:43], v[202:205], v[136:139]
	v_mfma_f32_16x16x32_bf16 v[124:127], v[24:27], v[214:217], v[124:127]
	v_mfma_f32_16x16x32_bf16 v[120:123], v[40:43], v[214:217], v[120:123]
	v_mfma_f32_16x16x32_bf16 v[108:111], v[24:27], v[222:225], v[108:111]
	v_mfma_f32_16x16x32_bf16 v[104:107], v[40:43], v[222:225], v[104:107]
	v_mfma_f32_16x16x32_bf16 v[92:95], v[24:27], v[244:247], v[92:95]
	v_mfma_f32_16x16x32_bf16 v[88:91], v[40:43], v[244:247], v[88:91]
	v_mfma_f32_16x16x32_bf16 v[140:143], v[28:31], v[206:209], v[140:143]
	v_mfma_f32_16x16x32_bf16 v[136:139], v[44:47], v[206:209], v[136:139]
	v_mfma_f32_16x16x32_bf16 v[124:127], v[28:31], v[218:221], v[124:127]
	v_mfma_f32_16x16x32_bf16 v[120:123], v[44:47], v[218:221], v[120:123]
	v_mfma_f32_16x16x32_bf16 v[108:111], v[28:31], v[240:243], v[108:111]
	v_mfma_f32_16x16x32_bf16 v[104:107], v[44:47], v[240:243], v[104:107]
	v_mfma_f32_16x16x32_bf16 v[92:95], v[28:31], v[248:251], v[92:95]
	v_mfma_f32_16x16x32_bf16 v[88:91], v[44:47], v[248:251], v[88:91]
	v_mfma_f32_16x16x32_bf16 v[132:135], v[186:189], v[202:205], v[132:135]
	v_mfma_f32_16x16x32_bf16 v[128:131], v[194:197], v[202:205], v[128:131]
	v_mfma_f32_16x16x32_bf16 v[116:119], v[186:189], v[214:217], v[116:119]
	v_mfma_f32_16x16x32_bf16 v[112:115], v[194:197], v[214:217], v[112:115]
	v_mfma_f32_16x16x32_bf16 v[100:103], v[186:189], v[222:225], v[100:103]
	v_mfma_f32_16x16x32_bf16 v[96:99], v[194:197], v[222:225], v[96:99]
	v_mfma_f32_16x16x32_bf16 v[84:87], v[186:189], v[244:247], v[84:87]
	v_mfma_f32_16x16x32_bf16 v[80:83], v[194:197], v[244:247], v[80:83]
	v_mfma_f32_16x16x32_bf16 v[132:135], v[190:193], v[206:209], v[132:135]
	v_mfma_f32_16x16x32_bf16 v[128:131], v[198:201], v[206:209], v[128:131]
	v_mfma_f32_16x16x32_bf16 v[116:119], v[190:193], v[218:221], v[116:119]
	v_mfma_f32_16x16x32_bf16 v[112:115], v[198:201], v[218:221], v[112:115]
	v_mfma_f32_16x16x32_bf16 v[100:103], v[190:193], v[240:243], v[100:103]
	v_mfma_f32_16x16x32_bf16 v[96:99], v[198:201], v[240:243], v[96:99]
	v_mfma_f32_16x16x32_bf16 v[84:87], v[190:193], v[248:251], v[84:87]
	v_mfma_f32_16x16x32_bf16 v[80:83], v[198:201], v[248:251], v[80:83]
	s_barrier
	s_setprio 0
	s_add_i32 s38, s38, s2
	v_lshl_add_u64 v[170:171], s[40:41], 0, v[146:147]
	s_mov_b32 m0, s38
	ds_read_b128 v[202:205], v184 offset:16384
	ds_read_b128 v[206:209], v184 offset:17408
	ds_read_b128 v[214:217], v184 offset:18432
	ds_read_b128 v[218:221], v184 offset:19456
	ds_read_b128 v[222:225], v184 offset:20480
	ds_read_b128 v[240:243], v184 offset:21504
	ds_read_b128 v[244:247], v184 offset:22528
	ds_read_b128 v[248:251], v184 offset:23552
	global_load_lds_dwordx4 v[170:171], off
	s_add_i32 m0, s38, 0x2000
	s_add_u32 s54, s40, 0x40000
	v_lshl_add_u64 v[210:211], s[40:41], 0, v[150:151]
	s_addc_u32 s55, s41, 0
	s_add_i32 s38, s56, s2
	global_load_lds_dwordx4 v[210:211], off
	v_lshl_add_u64 v[252:253], s[54:55], 0, v[146:147]
	s_mov_b32 m0, s38
	v_lshl_add_u64 v[234:235], s[14:15], 0, v[148:149]
	global_load_lds_dwordx4 v[252:253], off
	v_lshl_add_u64 v[252:253], s[54:55], 0, v[150:151]
	s_add_i32 m0, s38, 0x2000
	s_nop 0
	global_load_lds_dwordx4 v[252:253], off
	v_lshl_add_u64 v[252:253], s[14:15], 0, v[144:145]
	s_mov_b32 m0, s3
	s_nop 0
	global_load_lds_dwordx4 v[252:253], off
	s_mov_b32 m0, s16
	s_nop 0
	global_load_lds_dwordx4 v[234:235], off
	s_waitcnt vmcnt(8)
	s_waitcnt lgkmcnt(0)
	s_setprio 1
	s_barrier
; #define PG8_STAGE(bufoff, gbase, voff) do { _Pragma("unroll") for (int _i = 0; _i < 2; ++_i) \
;         __builtin_amdgcn_global_load_lds((const unsigned*)((const char*)(gbase) + (voff)[_i]), (PG8_LAS unsigned*)(lds + (bufoff) + ldsw + _i * 8192), 16, 0, 0); } while (0)
; #define PG8_LDA(dst, b, h) do { _Pragma("unroll") for (int m = 0; m < 4; ++m) _Pragma("unroll") for (int k = 0; k < 2; ++k) dst[m][k] = *(const PG8_LAS bf16x8*)(lds + PG8_SA(b, h) + aoff + m * 2048 + k * 1024); } while (0)
; #define PG8_LDB(dst, b, h) do { _Pragma("unroll") for (int n = 0; n < 2; ++n) _Pragma("unroll") for (int k = 0; k < 2; ++k) dst[n][k] = *(const PG8_LAS bf16x8*)(lds + PG8_SB(b, h) + boff + n * 2048 + k * 1024); } while (0)
; #define PG8_MMA(ai, bj, At, Bt) do { __builtin_amdgcn_s_setprio(1); _Pragma("unroll") for (int m = 0; m < 4; ++m) _Pragma("unroll") for (int n = 0; n < 2; ++n) _Pragma("unroll") for (int k = 0; k < 2; ++k) \
;         acc[ai][bj][m][n] = __builtin_amdgcn_mfma_f32_16x16x32_bf16(Bt[n][k], At[m][k], acc[ai][bj][m][n], 0, 0, 0); __builtin_amdgcn_s_setprio(0); } while (0)
; #define PG8_WAIT_V(n) asm volatile("s_waitcnt vmcnt(" #n ")" ::: "memory")
; #define PG8_WAIT_L(n) asm volatile("s_waitcnt lgkmcnt(" #n ")" ::: "memory")
; #define PG8_BAR __builtin_amdgcn_s_barrier()
; #define PG8_SCHED __builtin_amdgcn_sched_barrier(0)
; template <class Epi, class Sched, bool ALIGN_EPI = false, bool SP2 = false>
; __device__ __forceinline__ void gemm_phase(PG8_LAS unsigned char* lds, const Gemm g, const Sched& S, const Epi& E) {
;     ...
;             PG8_WAIT_V(8); PG8_WAIT_L(0); PG8_BAR; PG8_MMA(1, 0, At, B0); PG8_MMA(1, 1, At, B1); PG8_BAR; PG8_SCHED;
;             PG8_LDB(B0, 1, 0); PG8_LDB(B1, 1, 1); PG8_SCHED; PG8_LDA(At, 1, 0); PG8_STAGE(PG8_SA(0, 1), a2 + hstepA, voffA);
;             PG8_WAIT_V(8); PG8_WAIT_L(0); PG8_BAR; PG8_MMA(0, 0, At, B0); PG8_MMA(0, 1, At, B1); PG8_BAR; PG8_SCHED;
	v_mfma_f32_16x16x32_bf16 v[76:79], v[24:27], v[202:205], v[76:79]
	v_mfma_f32_16x16x32_bf16 v[72:75], v[40:43], v[202:205], v[72:75]
	v_mfma_f32_16x16x32_bf16 v[60:63], v[24:27], v[214:217], v[60:63]
	v_mfma_f32_16x16x32_bf16 v[56:59], v[40:43], v[214:217], v[56:59]
	v_mfma_f32_16x16x32_bf16 v[36:39], v[24:27], v[222:225], v[36:39]
	v_mfma_f32_16x16x32_bf16 v[32:35], v[40:43], v[222:225], v[32:35]
	v_mfma_f32_16x16x32_bf16 v[12:15], v[24:27], v[244:247], v[12:15]
	v_mfma_f32_16x16x32_bf16 v[8:11], v[40:43], v[244:247], v[8:11]
	v_mfma_f32_16x16x32_bf16 v[76:79], v[28:31], v[206:209], v[76:79]
	v_mfma_f32_16x16x32_bf16 v[72:75], v[44:47], v[206:209], v[72:75]
	v_mfma_f32_16x16x32_bf16 v[60:63], v[28:31], v[218:221], v[60:63]
	v_mfma_f32_16x16x32_bf16 v[56:59], v[44:47], v[218:221], v[56:59]
	v_mfma_f32_16x16x32_bf16 v[36:39], v[28:31], v[240:243], v[36:39]
	v_mfma_f32_16x16x32_bf16 v[32:35], v[44:47], v[240:243], v[32:35]
	v_mfma_f32_16x16x32_bf16 v[12:15], v[28:31], v[248:251], v[12:15]
	v_mfma_f32_16x16x32_bf16 v[8:11], v[44:47], v[248:251], v[8:11]
	v_mfma_f32_16x16x32_bf16 v[20:23], v[186:189], v[222:225], v[20:23]
	v_mfma_f32_16x16x32_bf16 v[16:19], v[194:197], v[222:225], v[16:19]
	v_mfma_f32_16x16x32_bf16 v[4:7], v[186:189], v[244:247], v[4:7]
	v_mfma_f32_16x16x32_bf16 v[0:3], v[194:197], v[244:247], v[0:3]
	v_mfma_f32_16x16x32_bf16 v[24:27], v[186:189], v[202:205], v[68:71]
	v_mfma_f32_16x16x32_bf16 v[28:31], v[194:197], v[202:205], v[64:67]
	v_mfma_f32_16x16x32_bf16 v[40:43], v[186:189], v[214:217], v[52:55]
	v_mfma_f32_16x16x32_bf16 v[44:47], v[194:197], v[214:217], v[48:51]
	v_mfma_f32_16x16x32_bf16 v[20:23], v[190:193], v[240:243], v[20:23]
	v_mfma_f32_16x16x32_bf16 v[16:19], v[198:201], v[240:243], v[16:19]
	v_mfma_f32_16x16x32_bf16 v[4:7], v[190:193], v[248:251], v[4:7]
	v_mfma_f32_16x16x32_bf16 v[0:3], v[198:201], v[248:251], v[0:3]
	v_mfma_f32_16x16x32_bf16 v[24:27], v[190:193], v[206:209], v[24:27]
	v_mfma_f32_16x16x32_bf16 v[28:31], v[198:201], v[206:209], v[28:31]
	v_mfma_f32_16x16x32_bf16 v[40:43], v[190:193], v[218:221], v[40:43]
	v_mfma_f32_16x16x32_bf16 v[44:47], v[198:201], v[218:221], v[44:47]
	s_barrier
	s_setprio 0
	s_add_i32 s38, 0, 0x18000
	s_add_i32 s54, 0, 0x1c000
	v_add_u32_e32 v68, s38, v174
	v_add_u32_e32 v157, s54, v174
	ds_read_b128 v[48:51], v68
	ds_read_b128 v[52:55], v68 offset:1024
	ds_read_b128 v[64:67], v68 offset:2048
	ds_read_b128 v[68:71], v68 offset:3072
	ds_read_b128 v[186:189], v157
	ds_read_b128 v[190:193], v157 offset:1024
	ds_read_b128 v[194:197], v157 offset:2048
	ds_read_b128 v[198:201], v157 offset:3072
	s_add_u32 s14, s14, 0x40000
	s_addc_u32 s15, s15, 0
	s_mov_b32 m0, s17
	v_lshl_add_u64 v[176:177], s[14:15], 0, v[144:145]
	ds_read_b128 v[202:205], v184 offset:32768
	ds_read_b128 v[206:209], v184 offset:33792
	ds_read_b128 v[214:217], v184 offset:34816
	ds_read_b128 v[218:221], v184 offset:35840
	ds_read_b128 v[222:225], v184 offset:36864
	ds_read_b128 v[240:243], v184 offset:37888
	ds_read_b128 v[244:247], v184 offset:38912
	ds_read_b128 v[248:251], v184 offset:39936
	global_load_lds_dwordx4 v[176:177], off
	v_lshl_add_u64 v[176:177], s[14:15], 0, v[148:149]
	s_mov_b32 m0, s20
	s_nop 0
	global_load_lds_dwordx4 v[176:177], off
	s_waitcnt vmcnt(8)
	s_waitcnt lgkmcnt(0)
	s_setprio 1
	s_barrier
	v_mfma_f32_16x16x32_bf16 v[140:143], v[48:51], v[202:205], v[140:143]
	v_mfma_f32_16x16x32_bf16 v[136:139], v[64:67], v[202:205], v[136:139]
	v_mfma_f32_16x16x32_bf16 v[124:127], v[48:51], v[214:217], v[124:127]
	v_mfma_f32_16x16x32_bf16 v[120:123], v[64:67], v[214:217], v[120:123]
	v_mfma_f32_16x16x32_bf16 v[108:111], v[48:51], v[222:225], v[108:111]
	v_mfma_f32_16x16x32_bf16 v[104:107], v[64:67], v[222:225], v[104:107]
	v_mfma_f32_16x16x32_bf16 v[92:95], v[48:51], v[244:247], v[92:95]
	v_mfma_f32_16x16x32_bf16 v[88:91], v[64:67], v[244:247], v[88:91]
	v_mfma_f32_16x16x32_bf16 v[140:143], v[52:55], v[206:209], v[140:143]
	v_mfma_f32_16x16x32_bf16 v[136:139], v[68:71], v[206:209], v[136:139]
	v_mfma_f32_16x16x32_bf16 v[124:127], v[52:55], v[218:221], v[124:127]
	v_mfma_f32_16x16x32_bf16 v[120:123], v[68:71], v[218:221], v[120:123]
	v_mfma_f32_16x16x32_bf16 v[108:111], v[52:55], v[240:243], v[108:111]
	v_mfma_f32_16x16x32_bf16 v[104:107], v[68:71], v[240:243], v[104:107]
	v_mfma_f32_16x16x32_bf16 v[92:95], v[52:55], v[248:251], v[92:95]
	v_mfma_f32_16x16x32_bf16 v[88:91], v[68:71], v[248:251], v[88:91]
	v_mfma_f32_16x16x32_bf16 v[132:135], v[186:189], v[202:205], v[132:135]
	v_mfma_f32_16x16x32_bf16 v[128:131], v[194:197], v[202:205], v[128:131]
	v_mfma_f32_16x16x32_bf16 v[116:119], v[186:189], v[214:217], v[116:119]
	v_mfma_f32_16x16x32_bf16 v[112:115], v[194:197], v[214:217], v[112:115]
	v_mfma_f32_16x16x32_bf16 v[100:103], v[186:189], v[222:225], v[100:103]
	v_mfma_f32_16x16x32_bf16 v[96:99], v[194:197], v[222:225], v[96:99]
	v_mfma_f32_16x16x32_bf16 v[84:87], v[186:189], v[244:247], v[84:87]
	v_mfma_f32_16x16x32_bf16 v[80:83], v[194:197], v[244:247], v[80:83]
	v_mfma_f32_16x16x32_bf16 v[132:135], v[190:193], v[206:209], v[132:135]
	v_mfma_f32_16x16x32_bf16 v[128:131], v[198:201], v[206:209], v[128:131]
	v_mfma_f32_16x16x32_bf16 v[116:119], v[190:193], v[218:221], v[116:119]
	v_mfma_f32_16x16x32_bf16 v[112:115], v[198:201], v[218:221], v[112:115]
	v_mfma_f32_16x16x32_bf16 v[100:103], v[190:193], v[240:243], v[100:103]
	v_mfma_f32_16x16x32_bf16 v[96:99], v[198:201], v[240:243], v[96:99]
	v_mfma_f32_16x16x32_bf16 v[84:87], v[190:193], v[248:251], v[84:87]
	v_mfma_f32_16x16x32_bf16 v[80:83], v[198:201], v[248:251], v[80:83]
	s_barrier
; #define PG8_STAGE(bufoff, gbase, voff) do { _Pragma("unroll") for (int _i = 0; _i < 2; ++_i) \
;         __builtin_amdgcn_global_load_lds((const unsigned*)((const char*)(gbase) + (voff)[_i]), (PG8_LAS unsigned*)(lds + (bufoff) + ldsw + _i * 8192), 16, 0, 0); } while (0)
; #define PG8_LDA(dst, b, h) do { _Pragma("unroll") for (int m = 0; m < 4; ++m) _Pragma("unroll") for (int k = 0; k < 2; ++k) dst[m][k] = *(const PG8_LAS bf16x8*)(lds + PG8_SA(b, h) + aoff + m * 2048 + k * 1024); } while (0)
; #define PG8_MMA(ai, bj, At, Bt) do { __builtin_amdgcn_s_setprio(1); _Pragma("unroll") for (int m = 0; m < 4; ++m) _Pragma("unroll") for (int n = 0; n < 2; ++n) _Pragma("unroll") for (int k = 0; k < 2; ++k) \
;         acc[ai][bj][m][n] = __builtin_amdgcn_mfma_f32_16x16x32_bf16(Bt[n][k], At[m][k], acc[ai][bj][m][n], 0, 0, 0); __builtin_amdgcn_s_setprio(0); } while (0)
; #define PG8_WAIT_V(n) asm volatile("s_waitcnt vmcnt(" #n ")" ::: "memory")
; #define PG8_WAIT_L(n) asm volatile("s_waitcnt lgkmcnt(" #n ")" ::: "memory")
; #define PG8_BAR __builtin_amdgcn_s_barrier()
; #define PG8_SCHED __builtin_amdgcn_sched_barrier(0)
; template <class Epi, class Sched, bool ALIGN_EPI = false, bool SP2 = false>
; __device__ __forceinline__ void gemm_phase(PG8_LAS unsigned char* lds, const Gemm g, const Sched& S, const Epi& E) {
;     ...
;         for (int t = 0; t < nt; t += 2) {
;     ...
;             PG8_LDA(At, 1, 1); PG8_STAGE(PG8_SB(1, 0), b3, voffB); PG8_STAGE(PG8_SB(1, 1), b3 + hstep, voffB); PG8_STAGE(PG8_SA(1, 0), a3, voffA);
;             PG8_WAIT_V(8); PG8_WAIT_L(0); PG8_BAR; PG8_MMA(1, 0, At, B0); PG8_MMA(1, 1, At, B1); PG8_BAR; PG8_SCHED;
;     ...
;         if constexpr (ALIGN_EPI) { if (wr == 0) PG8_BAR; }
	s_setprio 0
	s_add_i32 s14, s38, s2
	v_lshl_add_u64 v[170:171], v[170:171], 0, s[22:23]
	s_mov_b32 m0, s14
	ds_read_b128 v[202:205], v184 offset:49152
	ds_read_b128 v[206:209], v184 offset:50176
	ds_read_b128 v[214:217], v184 offset:51200
	ds_read_b128 v[218:221], v184 offset:52224
	ds_read_b128 v[222:225], v184 offset:53248
	ds_read_b128 v[240:243], v184 offset:54272
	ds_read_b128 v[244:247], v184 offset:55296
	ds_read_b128 v[248:251], v184 offset:56320
	global_load_lds_dwordx4 v[170:171], off
	s_add_i32 m0, s14, 0x2000
	s_add_u32 s14, s40, 0x40080
	v_lshl_add_u64 v[170:171], v[210:211], 0, s[22:23]
	s_addc_u32 s15, s41, 0
	s_add_i32 s38, s54, s2
	global_load_lds_dwordx4 v[170:171], off
	v_lshl_add_u64 v[170:171], s[14:15], 0, v[146:147]
	s_mov_b32 m0, s38
	s_nop 0
	global_load_lds_dwordx4 v[170:171], off
	v_lshl_add_u64 v[170:171], s[14:15], 0, v[150:151]
	s_add_i32 m0, s38, 0x2000
	s_nop 0
	global_load_lds_dwordx4 v[170:171], off
	v_lshl_add_u64 v[170:171], v[252:253], 0, s[22:23]
	s_mov_b32 m0, s29
	s_nop 0
	global_load_lds_dwordx4 v[170:171], off
	v_lshl_add_u64 v[170:171], v[234:235], 0, s[22:23]
	s_mov_b32 m0, s31
	s_nop 0
	global_load_lds_dwordx4 v[170:171], off
	s_waitcnt vmcnt(8)
	s_waitcnt lgkmcnt(0)
	s_setprio 1
	s_barrier
	v_mfma_f32_16x16x32_bf16 v[76:79], v[48:51], v[202:205], v[76:79]
	v_mfma_f32_16x16x32_bf16 v[72:75], v[64:67], v[202:205], v[72:75]
	v_mfma_f32_16x16x32_bf16 v[60:63], v[48:51], v[214:217], v[60:63]
	v_mfma_f32_16x16x32_bf16 v[56:59], v[64:67], v[214:217], v[56:59]
	v_mfma_f32_16x16x32_bf16 v[36:39], v[48:51], v[222:225], v[36:39]
	v_mfma_f32_16x16x32_bf16 v[32:35], v[64:67], v[222:225], v[32:35]
	v_mfma_f32_16x16x32_bf16 v[12:15], v[48:51], v[244:247], v[12:15]
	v_mfma_f32_16x16x32_bf16 v[8:11], v[64:67], v[244:247], v[8:11]
	v_mfma_f32_16x16x32_bf16 v[76:79], v[52:55], v[206:209], v[76:79]
	v_mfma_f32_16x16x32_bf16 v[72:75], v[68:71], v[206:209], v[72:75]
	v_mfma_f32_16x16x32_bf16 v[60:63], v[52:55], v[218:221], v[60:63]
	v_mfma_f32_16x16x32_bf16 v[56:59], v[68:71], v[218:221], v[56:59]
	v_mfma_f32_16x16x32_bf16 v[36:39], v[52:55], v[240:243], v[36:39]
	v_mfma_f32_16x16x32_bf16 v[32:35], v[68:71], v[240:243], v[32:35]
	v_mfma_f32_16x16x32_bf16 v[12:15], v[52:55], v[248:251], v[12:15]
	v_mfma_f32_16x16x32_bf16 v[8:11], v[68:71], v[248:251], v[8:11]
	v_mfma_f32_16x16x32_bf16 v[24:27], v[186:189], v[202:205], v[24:27]
	v_mfma_f32_16x16x32_bf16 v[68:71], v[190:193], v[206:209], v[24:27]
	v_mfma_f32_16x16x32_bf16 v[24:27], v[194:197], v[202:205], v[28:31]
	v_mfma_f32_16x16x32_bf16 v[64:67], v[198:201], v[206:209], v[24:27]
	v_mfma_f32_16x16x32_bf16 v[24:27], v[186:189], v[214:217], v[40:43]
	v_mfma_f32_16x16x32_bf16 v[52:55], v[190:193], v[218:221], v[24:27]
	v_mfma_f32_16x16x32_bf16 v[24:27], v[194:197], v[214:217], v[44:47]
	v_mfma_f32_16x16x32_bf16 v[20:23], v[186:189], v[222:225], v[20:23]
	v_mfma_f32_16x16x32_bf16 v[16:19], v[194:197], v[222:225], v[16:19]
	v_mfma_f32_16x16x32_bf16 v[4:7], v[186:189], v[244:247], v[4:7]
	v_mfma_f32_16x16x32_bf16 v[0:3], v[194:197], v[244:247], v[0:3]
	v_mfma_f32_16x16x32_bf16 v[48:51], v[198:201], v[218:221], v[24:27]
	v_mfma_f32_16x16x32_bf16 v[20:23], v[190:193], v[240:243], v[20:23]
	v_mfma_f32_16x16x32_bf16 v[16:19], v[198:201], v[240:243], v[16:19]
	v_mfma_f32_16x16x32_bf16 v[4:7], v[190:193], v[248:251], v[4:7]
	v_mfma_f32_16x16x32_bf16 v[0:3], v[198:201], v[248:251], v[0:3]
	s_barrier
	s_setprio 0
	s_add_i32 s52, s52, 2
	s_add_u32 s82, s82, 0x100
	s_addc_u32 s83, s83, 0
	s_add_u32 s34, s34, 0x100
	s_addc_u32 s36, s36, 0
	s_cmp_gt_u32 s52, 13
	s_cbranch_scc0 .LBB0_53
	s_and_b64 vcc, exec, s[72:73]
	s_cbranch_vccz .LBB0_56
	s_barrier

; #define PG8_STAGE(bufoff, gbase, voff) do { _Pragma("unroll") for (int _i = 0; _i < 2; ++_i) \
;         __builtin_amdgcn_global_load_lds((const unsigned*)((const char*)(gbase) + (voff)[_i]), (PG8_LAS unsigned*)(lds + (bufoff) + ldsw + _i * 8192), 16, 0, 0); } while (0)
; #define PG8_LDA(dst, b, h) do { _Pragma("unroll") for (int m = 0; m < 4; ++m) _Pragma("unroll") for (int k = 0; k < 2; ++k) dst[m][k] = *(const PG8_LAS bf16x8*)(lds + PG8_SA(b, h) + aoff + m * 2048 + k * 1024); } while (0)
; #define PG8_LDB(dst, b, h) do { _Pragma("unroll") for (int n = 0; n < 2; ++n) _Pragma("unroll") for (int k = 0; k < 2; ++k) dst[n][k] = *(const PG8_LAS bf16x8*)(lds + PG8_SB(b, h) + boff + n * 2048 + k * 1024); } while (0)
; #define PG8_WAIT_V(n) asm volatile("s_waitcnt vmcnt(" #n ")" ::: "memory")
; #define PG8_WAIT_L(n) asm volatile("s_waitcnt lgkmcnt(" #n ")" ::: "memory")
; #define PG8_BAR __builtin_amdgcn_s_barrier()
; #define PG8_SCHED __builtin_amdgcn_sched_barrier(0)
; template <class Epi, class Sched, bool ALIGN_EPI = false, bool SP2 = false>
; __device__ __forceinline__ void gemm_phase(PG8_LAS unsigned char* lds, const Gemm g, const Sched& S, const Epi& E) {
;     ...
;             const char* a1 = cA + (g.gstrA ? (size_t)(t >> 2) * g.gstrA + (size_t)(t & 3) * kstep : (size_t)t * kstep) + kstep;
;             const char* a2 = last ? nA : cA + (g.gstrA ? (size_t)((t + 2) >> 2) * g.gstrA + (size_t)((t + 2) & 3) * kstep : (size_t)(t + 2) * kstep); const char* b2 = last ? nB : cB + (size_t)(t + 2) * kstep;
;             const char* a3 = a2 + kstep; const char* b3 = b2 + kstep;
;             if (last && has_next) S.a_ready(nxt);
;             if constexpr (Epi::HAS_PREFETCH) { if (t == nt - 4) E.prefetch(cur, tid, wid); }
;             if constexpr (SP2) {
;             PG8_LDB(B0, 0, 0); PG8_LDB(B1, 0, 1); PG8_SCHED; PG8_LDA(At, 0, 0); PG8_STAGE(PG8_SA(1, 1), a1 + hstepA, voffA);
;             PG8_WAIT_V(8); PG8_WAIT_L(0); PG8_BAR; PG8_MMA(0, 0, At, B0); PG8_MMA(0, 1, At, B1); PG8_BAR; PG8_SCHED;
;             PG8_LDA(At, 0, 1); PG8_STAGE(PG8_SB(0, 0), b2, voffB); PG8_STAGE(PG8_SB(0, 1), b2 + hstep, voffB); PG8_STAGE(PG8_SA(0, 0), a2, voffA);
;             PG8_WAIT_V(8); PG8_WAIT_L(0); PG8_BAR; PG8_MMA(1, 0, At, B0); PG8_MMA(1, 1, At, B1); PG8_BAR; PG8_SCHED;
.LBB0_119:
	s_add_u32 s14, s74, 0xfffc0080
	s_addc_u32 s15, s75, -1
	s_add_i32 s35, 0, 0x10000
	s_cmp_eq_u32 s34, 12
	s_cselect_b32 s15, s24, s15
	s_cselect_b32 s14, s26, s14
	s_cselect_b32 s41, s28, s31
	s_cselect_b32 s40, s29, s30
	s_add_i32 s38, 0, 0x14000
	v_add_u32_e32 v76, s35, v157
	v_add_u32_e32 v154, s38, v157
	ds_read_b128 v[60:63], v76
	ds_read_b128 v[68:71], v76 offset:1024
	ds_read_b128 v[72:75], v76 offset:2048
	ds_read_b128 v[76:79], v76 offset:3072
	ds_read_b128 v[170:173], v154
	ds_read_b128 v[174:177], v154 offset:1024
	ds_read_b128 v[178:181], v154 offset:2048
	ds_read_b128 v[182:185], v154 offset:3072
	v_lshl_add_u64 v[154:155], s[74:75], 0, v[150:151]
	s_add_i32 m0, s3, 0xc000
	ds_read_b128 v[186:189], v168
	ds_read_b128 v[190:193], v168 offset:1024
	ds_read_b128 v[194:197], v168 offset:2048
	ds_read_b128 v[198:201], v168 offset:3072
	ds_read_b128 v[202:205], v168 offset:4096
	ds_read_b128 v[206:209], v168 offset:5120
	ds_read_b128 v[214:217], v168 offset:6144
	ds_read_b128 v[218:221], v168 offset:7168
	global_load_lds_dwordx4 v[154:155], off
	v_lshl_add_u64 v[154:155], s[74:75], 0, v[152:153]
	s_add_i32 m0, s3, 0xe000
	s_nop 0
	global_load_lds_dwordx4 v[154:155], off
	s_waitcnt vmcnt(8)
	s_waitcnt lgkmcnt(0)
	s_setprio 1
	s_barrier
	v_mfma_f32_16x16x32_bf16 v[140:143], v[60:63], v[186:189], v[140:143]
	v_mfma_f32_16x16x32_bf16 v[136:139], v[72:75], v[186:189], v[136:139]
	v_mfma_f32_16x16x32_bf16 v[124:127], v[60:63], v[194:197], v[124:127]
	v_mfma_f32_16x16x32_bf16 v[120:123], v[72:75], v[194:197], v[120:123]
	v_mfma_f32_16x16x32_bf16 v[108:111], v[60:63], v[202:205], v[108:111]
	v_mfma_f32_16x16x32_bf16 v[104:107], v[72:75], v[202:205], v[104:107]
	v_mfma_f32_16x16x32_bf16 v[92:95], v[60:63], v[214:217], v[92:95]
	v_mfma_f32_16x16x32_bf16 v[88:91], v[72:75], v[214:217], v[88:91]
	v_mfma_f32_16x16x32_bf16 v[140:143], v[68:71], v[190:193], v[140:143]
	v_mfma_f32_16x16x32_bf16 v[136:139], v[76:79], v[190:193], v[136:139]
	v_mfma_f32_16x16x32_bf16 v[124:127], v[68:71], v[198:201], v[124:127]
	v_mfma_f32_16x16x32_bf16 v[120:123], v[76:79], v[198:201], v[120:123]
	v_mfma_f32_16x16x32_bf16 v[108:111], v[68:71], v[206:209], v[108:111]
	v_mfma_f32_16x16x32_bf16 v[104:107], v[76:79], v[206:209], v[104:107]
	v_mfma_f32_16x16x32_bf16 v[92:95], v[68:71], v[218:221], v[92:95]
	v_mfma_f32_16x16x32_bf16 v[88:91], v[76:79], v[218:221], v[88:91]
	v_mfma_f32_16x16x32_bf16 v[132:135], v[170:173], v[186:189], v[132:135]
	v_mfma_f32_16x16x32_bf16 v[128:131], v[178:181], v[186:189], v[128:131]
	v_mfma_f32_16x16x32_bf16 v[116:119], v[170:173], v[194:197], v[116:119]
	v_mfma_f32_16x16x32_bf16 v[112:115], v[178:181], v[194:197], v[112:115]
	v_mfma_f32_16x16x32_bf16 v[100:103], v[170:173], v[202:205], v[100:103]
	v_mfma_f32_16x16x32_bf16 v[96:99], v[178:181], v[202:205], v[96:99]
	v_mfma_f32_16x16x32_bf16 v[84:87], v[170:173], v[214:217], v[84:87]
	v_mfma_f32_16x16x32_bf16 v[80:83], v[178:181], v[214:217], v[80:83]
	v_mfma_f32_16x16x32_bf16 v[132:135], v[174:177], v[190:193], v[132:135]
	v_mfma_f32_16x16x32_bf16 v[128:131], v[182:185], v[190:193], v[128:131]
	v_mfma_f32_16x16x32_bf16 v[116:119], v[174:177], v[198:201], v[116:119]
	v_mfma_f32_16x16x32_bf16 v[112:115], v[182:185], v[198:201], v[112:115]
	v_mfma_f32_16x16x32_bf16 v[100:103], v[174:177], v[206:209], v[100:103]
	v_mfma_f32_16x16x32_bf16 v[96:99], v[182:185], v[206:209], v[96:99]
	v_mfma_f32_16x16x32_bf16 v[84:87], v[174:177], v[218:221], v[84:87]
	v_mfma_f32_16x16x32_bf16 v[80:83], v[182:185], v[218:221], v[80:83]
	s_barrier
	s_setprio 0
	s_add_i32 s35, s35, s0
	v_lshl_add_u64 v[154:155], s[40:41], 0, v[212:213]
	s_mov_b32 m0, s35
	ds_read_b128 v[186:189], v168 offset:16384
	ds_read_b128 v[190:193], v168 offset:17408
	ds_read_b128 v[194:197], v168 offset:18432
	ds_read_b128 v[198:201], v168 offset:19456
	ds_read_b128 v[202:205], v168 offset:20480
	ds_read_b128 v[206:209], v168 offset:21504
	ds_read_b128 v[214:217], v168 offset:22528
	ds_read_b128 v[218:221], v168 offset:23552
	global_load_lds_dwordx4 v[154:155], off
	s_add_i32 m0, s35, 0x2000
	s_add_u32 s36, s40, 0x40000
	v_lshl_add_u64 v[210:211], s[40:41], 0, v[148:149]
	s_addc_u32 s37, s41, 0
	s_add_i32 s35, s38, s0
	global_load_lds_dwordx4 v[210:211], off
	v_lshl_add_u64 v[222:223], s[36:37], 0, v[212:213]
	s_mov_b32 m0, s35
	v_lshl_add_u64 v[224:225], s[14:15], 0, v[146:147]
	global_load_lds_dwordx4 v[222:223], off
	v_lshl_add_u64 v[222:223], s[36:37], 0, v[148:149]
	s_add_i32 m0, s35, 0x2000
	s_nop 0
	global_load_lds_dwordx4 v[222:223], off
	v_lshl_add_u64 v[222:223], s[14:15], 0, v[144:145]
	s_mov_b32 m0, s3
	s_nop 0
	global_load_lds_dwordx4 v[222:223], off
	s_mov_b32 m0, s16
	s_nop 0
	global_load_lds_dwordx4 v[224:225], off
	s_waitcnt vmcnt(8)
	s_waitcnt lgkmcnt(0)
	s_setprio 1
	s_barrier
; #define PG8_STAGE(bufoff, gbase, voff) do { _Pragma("unroll") for (int _i = 0; _i < 2; ++_i) \
;         __builtin_amdgcn_global_load_lds((const unsigned*)((const char*)(gbase) + (voff)[_i]), (PG8_LAS unsigned*)(lds + (bufoff) + ldsw + _i * 8192), 16, 0, 0); } while (0)
; #define PG8_LDA(dst, b, h) do { _Pragma("unroll") for (int m = 0; m < 4; ++m) _Pragma("unroll") for (int k = 0; k < 2; ++k) dst[m][k] = *(const PG8_LAS bf16x8*)(lds + PG8_SA(b, h) + aoff + m * 2048 + k * 1024); } while (0)
; #define PG8_LDB(dst, b, h) do { _Pragma("unroll") for (int n = 0; n < 2; ++n) _Pragma("unroll") for (int k = 0; k < 2; ++k) dst[n][k] = *(const PG8_LAS bf16x8*)(lds + PG8_SB(b, h) + boff + n * 2048 + k * 1024); } while (0)
; #define PG8_MMA(ai, bj, At, Bt) do { __builtin_amdgcn_s_setprio(1); _Pragma("unroll") for (int m = 0; m < 4; ++m) _Pragma("unroll") for (int n = 0; n < 2; ++n) _Pragma("unroll") for (int k = 0; k < 2; ++k) \
;         acc[ai][bj][m][n] = __builtin_amdgcn_mfma_f32_16x16x32_bf16(Bt[n][k], At[m][k], acc[ai][bj][m][n], 0, 0, 0); __builtin_amdgcn_s_setprio(0); } while (0)
; #define PG8_WAIT_V(n) asm volatile("s_waitcnt vmcnt(" #n ")" ::: "memory")
; #define PG8_WAIT_L(n) asm volatile("s_waitcnt lgkmcnt(" #n ")" ::: "memory")
; #define PG8_BAR __builtin_amdgcn_s_barrier()
; #define PG8_SCHED __builtin_amdgcn_sched_barrier(0)
; template <class Epi, class Sched, bool ALIGN_EPI = false, bool SP2 = false>
; __device__ __forceinline__ void gemm_phase(PG8_LAS unsigned char* lds, const Gemm g, const Sched& S, const Epi& E) {
;     ...
;             PG8_WAIT_V(8); PG8_WAIT_L(0); PG8_BAR; PG8_MMA(1, 0, At, B0); PG8_MMA(1, 1, At, B1); PG8_BAR; PG8_SCHED;
;             PG8_LDB(B0, 1, 0); PG8_LDB(B1, 1, 1); PG8_SCHED; PG8_LDA(At, 1, 0); PG8_STAGE(PG8_SA(0, 1), a2 + hstepA, voffA);
;             PG8_WAIT_V(8); PG8_WAIT_L(0); PG8_BAR; PG8_MMA(0, 0, At, B0); PG8_MMA(0, 1, At, B1); PG8_BAR; PG8_SCHED;
	v_mfma_f32_16x16x32_bf16 v[64:67], v[60:63], v[186:189], v[64:67]
	v_mfma_f32_16x16x32_bf16 v[56:59], v[72:75], v[186:189], v[56:59]
	v_mfma_f32_16x16x32_bf16 v[44:47], v[60:63], v[194:197], v[44:47]
	v_mfma_f32_16x16x32_bf16 v[40:43], v[72:75], v[194:197], v[40:43]
	v_mfma_f32_16x16x32_bf16 v[28:31], v[60:63], v[202:205], v[28:31]
	v_mfma_f32_16x16x32_bf16 v[24:27], v[72:75], v[202:205], v[24:27]
	v_mfma_f32_16x16x32_bf16 v[12:15], v[60:63], v[214:217], v[12:15]
	v_mfma_f32_16x16x32_bf16 v[8:11], v[72:75], v[214:217], v[8:11]
	v_mfma_f32_16x16x32_bf16 v[64:67], v[68:71], v[190:193], v[64:67]
	v_mfma_f32_16x16x32_bf16 v[56:59], v[76:79], v[190:193], v[56:59]
	v_mfma_f32_16x16x32_bf16 v[44:47], v[68:71], v[198:201], v[44:47]
	v_mfma_f32_16x16x32_bf16 v[40:43], v[76:79], v[198:201], v[40:43]
	v_mfma_f32_16x16x32_bf16 v[28:31], v[68:71], v[206:209], v[28:31]
	v_mfma_f32_16x16x32_bf16 v[24:27], v[76:79], v[206:209], v[24:27]
	v_mfma_f32_16x16x32_bf16 v[12:15], v[68:71], v[218:221], v[12:15]
	v_mfma_f32_16x16x32_bf16 v[8:11], v[76:79], v[218:221], v[8:11]
	v_mfma_f32_16x16x32_bf16 v[52:55], v[170:173], v[186:189], v[52:55]
	v_mfma_f32_16x16x32_bf16 v[48:51], v[178:181], v[186:189], v[48:51]
	v_mfma_f32_16x16x32_bf16 v[36:39], v[170:173], v[194:197], v[36:39]
	v_mfma_f32_16x16x32_bf16 v[32:35], v[178:181], v[194:197], v[32:35]
	v_mfma_f32_16x16x32_bf16 v[20:23], v[170:173], v[202:205], v[20:23]
	v_mfma_f32_16x16x32_bf16 v[16:19], v[178:181], v[202:205], v[16:19]
	v_mfma_f32_16x16x32_bf16 v[4:7], v[170:173], v[214:217], v[4:7]
	v_mfma_f32_16x16x32_bf16 v[0:3], v[178:181], v[214:217], v[0:3]
	v_mfma_f32_16x16x32_bf16 v[52:55], v[174:177], v[190:193], v[52:55]
	v_mfma_f32_16x16x32_bf16 v[48:51], v[182:185], v[190:193], v[48:51]
	v_mfma_f32_16x16x32_bf16 v[36:39], v[174:177], v[198:201], v[36:39]
	v_mfma_f32_16x16x32_bf16 v[32:35], v[182:185], v[198:201], v[32:35]
	v_mfma_f32_16x16x32_bf16 v[20:23], v[174:177], v[206:209], v[20:23]
	v_mfma_f32_16x16x32_bf16 v[16:19], v[182:185], v[206:209], v[16:19]
	v_mfma_f32_16x16x32_bf16 v[4:7], v[174:177], v[218:221], v[4:7]
	v_mfma_f32_16x16x32_bf16 v[0:3], v[182:185], v[218:221], v[0:3]
	s_barrier
	s_setprio 0
	s_add_i32 s35, 0, 0x18000
	s_add_i32 s36, 0, 0x1c000
	v_add_u32_e32 v76, s35, v157
	v_add_u32_e32 v169, s36, v157
	ds_read_b128 v[60:63], v76
	ds_read_b128 v[68:71], v76 offset:1024
	ds_read_b128 v[72:75], v76 offset:2048
	ds_read_b128 v[76:79], v76 offset:3072
	ds_read_b128 v[170:173], v169
	ds_read_b128 v[174:177], v169 offset:1024
	ds_read_b128 v[178:181], v169 offset:2048
	ds_read_b128 v[182:185], v169 offset:3072
	s_add_u32 s14, s14, 0x40000
	s_addc_u32 s15, s15, 0
	s_mov_b32 m0, s17
	v_lshl_add_u64 v[240:241], s[14:15], 0, v[144:145]
	ds_read_b128 v[186:189], v168 offset:32768
	ds_read_b128 v[190:193], v168 offset:33792
	ds_read_b128 v[194:197], v168 offset:34816
	ds_read_b128 v[198:201], v168 offset:35840
	ds_read_b128 v[202:205], v168 offset:36864
	ds_read_b128 v[206:209], v168 offset:37888
	ds_read_b128 v[214:217], v168 offset:38912
	ds_read_b128 v[218:221], v168 offset:39936
	global_load_lds_dwordx4 v[240:241], off
	v_lshl_add_u64 v[240:241], s[14:15], 0, v[146:147]
	s_mov_b32 m0, s18
	s_nop 0
	global_load_lds_dwordx4 v[240:241], off
	s_waitcnt vmcnt(8)
	s_waitcnt lgkmcnt(0)
	s_setprio 1
	s_barrier
	v_mfma_f32_16x16x32_bf16 v[140:143], v[60:63], v[186:189], v[140:143]
	v_mfma_f32_16x16x32_bf16 v[136:139], v[72:75], v[186:189], v[136:139]
	v_mfma_f32_16x16x32_bf16 v[124:127], v[60:63], v[194:197], v[124:127]
	v_mfma_f32_16x16x32_bf16 v[120:123], v[72:75], v[194:197], v[120:123]
	v_mfma_f32_16x16x32_bf16 v[108:111], v[60:63], v[202:205], v[108:111]
	v_mfma_f32_16x16x32_bf16 v[104:107], v[72:75], v[202:205], v[104:107]
	v_mfma_f32_16x16x32_bf16 v[92:95], v[60:63], v[214:217], v[92:95]
	v_mfma_f32_16x16x32_bf16 v[88:91], v[72:75], v[214:217], v[88:91]
	v_mfma_f32_16x16x32_bf16 v[140:143], v[68:71], v[190:193], v[140:143]
	v_mfma_f32_16x16x32_bf16 v[136:139], v[76:79], v[190:193], v[136:139]
	v_mfma_f32_16x16x32_bf16 v[124:127], v[68:71], v[198:201], v[124:127]
	v_mfma_f32_16x16x32_bf16 v[120:123], v[76:79], v[198:201], v[120:123]
	v_mfma_f32_16x16x32_bf16 v[108:111], v[68:71], v[206:209], v[108:111]
	v_mfma_f32_16x16x32_bf16 v[104:107], v[76:79], v[206:209], v[104:107]
	v_mfma_f32_16x16x32_bf16 v[92:95], v[68:71], v[218:221], v[92:95]
	v_mfma_f32_16x16x32_bf16 v[88:91], v[76:79], v[218:221], v[88:91]
	v_mfma_f32_16x16x32_bf16 v[132:135], v[170:173], v[186:189], v[132:135]
	v_mfma_f32_16x16x32_bf16 v[128:131], v[178:181], v[186:189], v[128:131]
	v_mfma_f32_16x16x32_bf16 v[116:119], v[170:173], v[194:197], v[116:119]
	v_mfma_f32_16x16x32_bf16 v[112:115], v[178:181], v[194:197], v[112:115]
	v_mfma_f32_16x16x32_bf16 v[100:103], v[170:173], v[202:205], v[100:103]
	v_mfma_f32_16x16x32_bf16 v[96:99], v[178:181], v[202:205], v[96:99]
	v_mfma_f32_16x16x32_bf16 v[84:87], v[170:173], v[214:217], v[84:87]
	v_mfma_f32_16x16x32_bf16 v[80:83], v[178:181], v[214:217], v[80:83]
	v_mfma_f32_16x16x32_bf16 v[132:135], v[174:177], v[190:193], v[132:135]
	v_mfma_f32_16x16x32_bf16 v[128:131], v[182:185], v[190:193], v[128:131]
	v_mfma_f32_16x16x32_bf16 v[116:119], v[174:177], v[198:201], v[116:119]
	v_mfma_f32_16x16x32_bf16 v[112:115], v[182:185], v[198:201], v[112:115]
	v_mfma_f32_16x16x32_bf16 v[100:103], v[174:177], v[206:209], v[100:103]
	v_mfma_f32_16x16x32_bf16 v[96:99], v[182:185], v[206:209], v[96:99]
	v_mfma_f32_16x16x32_bf16 v[84:87], v[174:177], v[218:221], v[84:87]
	v_mfma_f32_16x16x32_bf16 v[80:83], v[182:185], v[218:221], v[80:83]
	s_barrier
; #define PG8_STAGE(bufoff, gbase, voff) do { _Pragma("unroll") for (int _i = 0; _i < 2; ++_i) \
;         __builtin_amdgcn_global_load_lds((const unsigned*)((const char*)(gbase) + (voff)[_i]), (PG8_LAS unsigned*)(lds + (bufoff) + ldsw + _i * 8192), 16, 0, 0); } while (0)
; #define PG8_LDA(dst, b, h) do { _Pragma("unroll") for (int m = 0; m < 4; ++m) _Pragma("unroll") for (int k = 0; k < 2; ++k) dst[m][k] = *(const PG8_LAS bf16x8*)(lds + PG8_SA(b, h) + aoff + m * 2048 + k * 1024); } while (0)
; #define PG8_MMA(ai, bj, At, Bt) do { __builtin_amdgcn_s_setprio(1); _Pragma("unroll") for (int m = 0; m < 4; ++m) _Pragma("unroll") for (int n = 0; n < 2; ++n) _Pragma("unroll") for (int k = 0; k < 2; ++k) \
;         acc[ai][bj][m][n] = __builtin_amdgcn_mfma_f32_16x16x32_bf16(Bt[n][k], At[m][k], acc[ai][bj][m][n], 0, 0, 0); __builtin_amdgcn_s_setprio(0); } while (0)
; #define PG8_WAIT_V(n) asm volatile("s_waitcnt vmcnt(" #n ")" ::: "memory")
; #define PG8_WAIT_L(n) asm volatile("s_waitcnt lgkmcnt(" #n ")" ::: "memory")
; #define PG8_BAR __builtin_amdgcn_s_barrier()
; #define PG8_SCHED __builtin_amdgcn_sched_barrier(0)
; template <class Epi, class Sched, bool ALIGN_EPI = false, bool SP2 = false>
; __device__ __forceinline__ void gemm_phase(PG8_LAS unsigned char* lds, const Gemm g, const Sched& S, const Epi& E) {
;     ...
;         for (int t = 0; t < nt; t += 2) {
;     ...
;             PG8_LDA(At, 1, 1); PG8_STAGE(PG8_SB(1, 0), b3, voffB); PG8_STAGE(PG8_SB(1, 1), b3 + hstep, voffB); PG8_STAGE(PG8_SA(1, 0), a3, voffA);
;             PG8_WAIT_V(8); PG8_WAIT_L(0); PG8_BAR; PG8_MMA(1, 0, At, B0); PG8_MMA(1, 1, At, B1); PG8_BAR; PG8_SCHED;
;     ...
;         if constexpr (ALIGN_EPI) { if (wr == 0) PG8_BAR; }
	s_setprio 0
	s_add_i32 s14, s35, s0
	v_lshl_add_u64 v[154:155], v[154:155], 0, s[22:23]
	s_mov_b32 m0, s14
	ds_read_b128 v[186:189], v168 offset:49152
	ds_read_b128 v[190:193], v168 offset:50176
	ds_read_b128 v[194:197], v168 offset:51200
	ds_read_b128 v[198:201], v168 offset:52224
	ds_read_b128 v[202:205], v168 offset:53248
	ds_read_b128 v[206:209], v168 offset:54272
	ds_read_b128 v[214:217], v168 offset:55296
	ds_read_b128 v[218:221], v168 offset:56320
	global_load_lds_dwordx4 v[154:155], off
	s_add_i32 m0, s14, 0x2000
	s_add_u32 s14, s40, 0x40080
	v_lshl_add_u64 v[154:155], v[210:211], 0, s[22:23]
	s_addc_u32 s15, s41, 0
	s_add_i32 s35, s36, s0
	global_load_lds_dwordx4 v[154:155], off
	v_lshl_add_u64 v[154:155], s[14:15], 0, v[212:213]
	s_mov_b32 m0, s35
	s_nop 0
	global_load_lds_dwordx4 v[154:155], off
	v_lshl_add_u64 v[154:155], s[14:15], 0, v[148:149]
	s_add_i32 m0, s35, 0x2000
	s_nop 0
	global_load_lds_dwordx4 v[154:155], off
	v_lshl_add_u64 v[154:155], v[222:223], 0, s[22:23]
	s_mov_b32 m0, s20
	s_nop 0
	global_load_lds_dwordx4 v[154:155], off
	v_lshl_add_u64 v[154:155], v[224:225], 0, s[22:23]
	s_mov_b32 m0, s21
	s_nop 0
	global_load_lds_dwordx4 v[154:155], off
	s_waitcnt vmcnt(8)
	s_waitcnt lgkmcnt(0)
	s_setprio 1
	s_barrier
	v_mfma_f32_16x16x32_bf16 v[64:67], v[60:63], v[186:189], v[64:67]
	v_mfma_f32_16x16x32_bf16 v[56:59], v[72:75], v[186:189], v[56:59]
	v_mfma_f32_16x16x32_bf16 v[44:47], v[60:63], v[194:197], v[44:47]
	v_mfma_f32_16x16x32_bf16 v[40:43], v[72:75], v[194:197], v[40:43]
	v_mfma_f32_16x16x32_bf16 v[28:31], v[60:63], v[202:205], v[28:31]
	v_mfma_f32_16x16x32_bf16 v[24:27], v[72:75], v[202:205], v[24:27]
	v_mfma_f32_16x16x32_bf16 v[12:15], v[60:63], v[214:217], v[12:15]
	v_mfma_f32_16x16x32_bf16 v[8:11], v[72:75], v[214:217], v[8:11]
	v_mfma_f32_16x16x32_bf16 v[64:67], v[68:71], v[190:193], v[64:67]
	v_mfma_f32_16x16x32_bf16 v[56:59], v[76:79], v[190:193], v[56:59]
	v_mfma_f32_16x16x32_bf16 v[44:47], v[68:71], v[198:201], v[44:47]
	v_mfma_f32_16x16x32_bf16 v[40:43], v[76:79], v[198:201], v[40:43]
	v_mfma_f32_16x16x32_bf16 v[28:31], v[68:71], v[206:209], v[28:31]
	v_mfma_f32_16x16x32_bf16 v[24:27], v[76:79], v[206:209], v[24:27]
	v_mfma_f32_16x16x32_bf16 v[12:15], v[68:71], v[218:221], v[12:15]
	v_mfma_f32_16x16x32_bf16 v[8:11], v[76:79], v[218:221], v[8:11]
	v_mfma_f32_16x16x32_bf16 v[52:55], v[170:173], v[186:189], v[52:55]
	v_mfma_f32_16x16x32_bf16 v[48:51], v[178:181], v[186:189], v[48:51]
	v_mfma_f32_16x16x32_bf16 v[36:39], v[170:173], v[194:197], v[36:39]
	v_mfma_f32_16x16x32_bf16 v[32:35], v[178:181], v[194:197], v[32:35]
	v_mfma_f32_16x16x32_bf16 v[20:23], v[170:173], v[202:205], v[20:23]
	v_mfma_f32_16x16x32_bf16 v[16:19], v[178:181], v[202:205], v[16:19]
	v_mfma_f32_16x16x32_bf16 v[4:7], v[170:173], v[214:217], v[4:7]
	v_mfma_f32_16x16x32_bf16 v[0:3], v[178:181], v[214:217], v[0:3]
	v_mfma_f32_16x16x32_bf16 v[52:55], v[174:177], v[190:193], v[52:55]
	v_mfma_f32_16x16x32_bf16 v[48:51], v[182:185], v[190:193], v[48:51]
	v_mfma_f32_16x16x32_bf16 v[36:39], v[174:177], v[198:201], v[36:39]
	v_mfma_f32_16x16x32_bf16 v[32:35], v[182:185], v[198:201], v[32:35]
	v_mfma_f32_16x16x32_bf16 v[20:23], v[174:177], v[206:209], v[20:23]
	v_mfma_f32_16x16x32_bf16 v[16:19], v[182:185], v[206:209], v[16:19]
	v_mfma_f32_16x16x32_bf16 v[4:7], v[174:177], v[218:221], v[4:7]
	v_mfma_f32_16x16x32_bf16 v[0:3], v[182:185], v[218:221], v[0:3]
	s_barrier
	s_setprio 0
	s_add_i32 s34, s34, 2
	s_add_u32 s74, s74, 0x100
	s_addc_u32 s75, s75, 0
	s_add_u32 s30, s30, 0x100
	s_addc_u32 s31, s31, 0
	s_cmp_gt_u32 s34, 13
	s_cbranch_scc0 .LBB0_119
	s_and_b64 vcc, exec, s[62:63]
	s_cbranch_vccz .LBB0_122
	s_barrier

; #define PG8_STAGE(bufoff, gbase, voff) do { _Pragma("unroll") for (int _i = 0; _i < 2; ++_i) \
;         __builtin_amdgcn_global_load_lds((const unsigned*)((const char*)(gbase) + (voff)[_i]), (PG8_LAS unsigned*)(lds + (bufoff) + ldsw + _i * 8192), 16, 0, 0); } while (0)
; #define PG8_LDA(dst, b, h) do { _Pragma("unroll") for (int m = 0; m < 4; ++m) _Pragma("unroll") for (int k = 0; k < 2; ++k) dst[m][k] = *(const PG8_LAS bf16x8*)(lds + PG8_SA(b, h) + aoff + m * 2048 + k * 1024); } while (0)
; #define PG8_LDB(dst, b, h) do { _Pragma("unroll") for (int n = 0; n < 2; ++n) _Pragma("unroll") for (int k = 0; k < 2; ++k) dst[n][k] = *(const PG8_LAS bf16x8*)(lds + PG8_SB(b, h) + boff + n * 2048 + k * 1024); } while (0)
; #define PG8_WAIT_V(n) asm volatile("s_waitcnt vmcnt(" #n ")" ::: "memory")
; #define PG8_WAIT_L(n) asm volatile("s_waitcnt lgkmcnt(" #n ")" ::: "memory")
; #define PG8_BAR __builtin_amdgcn_s_barrier()
; #define PG8_SCHED __builtin_amdgcn_sched_barrier(0)
; template <class Epi, class Sched, bool ALIGN_EPI = false, bool SP2 = false>
; __device__ __forceinline__ void gemm_phase(PG8_LAS unsigned char* lds, const Gemm g, const Sched& S, const Epi& E) {
;     ...
;             const char* a1 = cA + (g.gstrA ? (size_t)(t >> 2) * g.gstrA + (size_t)(t & 3) * kstep : (size_t)t * kstep) + kstep;
;             const char* a2 = last ? nA : cA + (g.gstrA ? (size_t)((t + 2) >> 2) * g.gstrA + (size_t)((t + 2) & 3) * kstep : (size_t)(t + 2) * kstep); const char* b2 = last ? nB : cB + (size_t)(t + 2) * kstep;
;             const char* a3 = a2 + kstep; const char* b3 = b2 + kstep;
;             if (last && has_next) S.a_ready(nxt);
;             if constexpr (Epi::HAS_PREFETCH) { if (t == nt - 4) E.prefetch(cur, tid, wid); }
;             if constexpr (SP2) {
;             PG8_LDB(B0, 0, 0); PG8_LDB(B1, 0, 1); PG8_SCHED; PG8_LDA(At, 0, 0); PG8_STAGE(PG8_SA(1, 1), a1 + hstepA, voffA);
;             PG8_WAIT_V(8); PG8_WAIT_L(0); PG8_BAR; PG8_MMA(0, 0, At, B0); PG8_MMA(0, 1, At, B1); PG8_BAR; PG8_SCHED;
;             PG8_LDA(At, 0, 1); PG8_STAGE(PG8_SB(0, 0), b2, voffB); PG8_STAGE(PG8_SB(0, 1), b2 + hstep, voffB); PG8_STAGE(PG8_SA(0, 0), a2, voffA);
;             PG8_WAIT_V(8); PG8_WAIT_L(0); PG8_BAR; PG8_MMA(1, 0, At, B0); PG8_MMA(1, 1, At, B1); PG8_BAR; PG8_SCHED;
.LBB0_183:
	s_add_u32 vcc_lo, s30, s40
	s_addc_u32 vcc_hi, s34, s41
	s_add_i32 s38, 0, 0x10000
	s_and_b64 s[12:13], exec, s[14:15]
	s_cselect_b32 s13, s91, vcc_hi
	s_cselect_b32 s12, s90, vcc_lo
	s_add_i32 vcc_lo, 0, 0x14000
	v_add_u32_e32 v140, s38, v240
	v_add_u32_e32 v156, vcc_lo, v240
	ds_read_b128 v[128:131], v140
	ds_read_b128 v[132:135], v140 offset:1024
	ds_read_b128 v[136:139], v140 offset:2048
	ds_read_b128 v[140:143], v140 offset:3072
	ds_read_b128 v[144:147], v156
	ds_read_b128 v[148:151], v156 offset:1024
	ds_read_b128 v[152:155], v156 offset:2048
	ds_read_b128 v[156:159], v156 offset:3072
	s_add_u32 s14, s24, s94
	s_addc_u32 s15, s26, s95
	v_lshl_add_u64 v[198:199], s[14:15], 0, v[192:193]
	v_lshl_add_u64 v[198:199], v[198:199], 0, s[22:23]
	s_add_i32 m0, s52, 0xc000
	ds_read_b128 v[160:163], v243
	ds_read_b128 v[164:167], v243 offset:1024
	ds_read_b128 v[168:171], v243 offset:2048
	ds_read_b128 v[172:175], v243 offset:3072
	ds_read_b128 v[176:179], v243 offset:4096
	ds_read_b128 v[180:183], v243 offset:5120
	ds_read_b128 v[184:187], v243 offset:6144
	ds_read_b128 v[188:191], v243 offset:7168
	global_load_lds_dwordx4 v[198:199], off
	v_lshl_add_u64 v[198:199], s[14:15], 0, v[194:195]
	v_lshl_add_u64 v[198:199], v[198:199], 0, s[22:23]
	s_add_i32 m0, s52, 0xe000
	s_nop 0
	global_load_lds_dwordx4 v[198:199], off
	s_waitcnt vmcnt(8)
	s_waitcnt lgkmcnt(0)
	s_setprio 1
	s_barrier
	v_mfma_f32_16x16x32_bf16 v[124:127], v[128:131], v[160:163], v[124:127]
	v_mfma_f32_16x16x32_bf16 v[120:123], v[136:139], v[160:163], v[120:123]
	v_mfma_f32_16x16x32_bf16 v[108:111], v[128:131], v[168:171], v[108:111]
	v_mfma_f32_16x16x32_bf16 v[104:107], v[136:139], v[168:171], v[104:107]
	v_mfma_f32_16x16x32_bf16 v[92:95], v[128:131], v[176:179], v[92:95]
	v_mfma_f32_16x16x32_bf16 v[88:91], v[136:139], v[176:179], v[88:91]
	v_mfma_f32_16x16x32_bf16 v[76:79], v[128:131], v[184:187], v[76:79]
	v_mfma_f32_16x16x32_bf16 v[72:75], v[136:139], v[184:187], v[72:75]
	v_mfma_f32_16x16x32_bf16 v[124:127], v[132:135], v[164:167], v[124:127]
	v_mfma_f32_16x16x32_bf16 v[120:123], v[140:143], v[164:167], v[120:123]
	v_mfma_f32_16x16x32_bf16 v[108:111], v[132:135], v[172:175], v[108:111]
	v_mfma_f32_16x16x32_bf16 v[104:107], v[140:143], v[172:175], v[104:107]
	v_mfma_f32_16x16x32_bf16 v[92:95], v[132:135], v[180:183], v[92:95]
	v_mfma_f32_16x16x32_bf16 v[88:91], v[140:143], v[180:183], v[88:91]
	v_mfma_f32_16x16x32_bf16 v[76:79], v[132:135], v[188:191], v[76:79]
	v_mfma_f32_16x16x32_bf16 v[72:75], v[140:143], v[188:191], v[72:75]
	v_mfma_f32_16x16x32_bf16 v[116:119], v[144:147], v[160:163], v[116:119]
	v_mfma_f32_16x16x32_bf16 v[112:115], v[152:155], v[160:163], v[112:115]
	v_mfma_f32_16x16x32_bf16 v[100:103], v[144:147], v[168:171], v[100:103]
	v_mfma_f32_16x16x32_bf16 v[96:99], v[152:155], v[168:171], v[96:99]
	v_mfma_f32_16x16x32_bf16 v[84:87], v[144:147], v[176:179], v[84:87]
	v_mfma_f32_16x16x32_bf16 v[80:83], v[152:155], v[176:179], v[80:83]
	v_mfma_f32_16x16x32_bf16 v[68:71], v[144:147], v[184:187], v[68:71]
	v_mfma_f32_16x16x32_bf16 v[64:67], v[152:155], v[184:187], v[64:67]
	v_mfma_f32_16x16x32_bf16 v[116:119], v[148:151], v[164:167], v[116:119]
	v_mfma_f32_16x16x32_bf16 v[112:115], v[156:159], v[164:167], v[112:115]
	v_mfma_f32_16x16x32_bf16 v[100:103], v[148:151], v[172:175], v[100:103]
	v_mfma_f32_16x16x32_bf16 v[96:99], v[156:159], v[172:175], v[96:99]
	v_mfma_f32_16x16x32_bf16 v[84:87], v[148:151], v[180:183], v[84:87]
	v_mfma_f32_16x16x32_bf16 v[80:83], v[156:159], v[180:183], v[80:83]
	v_mfma_f32_16x16x32_bf16 v[68:71], v[148:151], v[188:191], v[68:71]
	v_mfma_f32_16x16x32_bf16 v[64:67], v[156:159], v[188:191], v[64:67]
	s_barrier
	s_setprio 0
	s_add_i32 s14, s38, s55
	v_lshl_add_u64 v[198:199], s[12:13], 0, v[212:213]
	s_mov_b32 m0, s14
	ds_read_b128 v[160:163], v243 offset:16384
	ds_read_b128 v[164:167], v243 offset:17408
	ds_read_b128 v[168:171], v243 offset:18432
	ds_read_b128 v[172:175], v243 offset:19456
	ds_read_b128 v[176:179], v243 offset:20480
	ds_read_b128 v[180:183], v243 offset:21504
	ds_read_b128 v[184:187], v243 offset:22528
	ds_read_b128 v[188:191], v243 offset:23552
	global_load_lds_dwordx4 v[198:199], off
	s_add_i32 m0, s14, 0x2000
	v_lshl_add_u64 v[200:201], s[12:13], 0, v[196:197]
	s_add_u32 s12, s12, s25
	s_addc_u32 s13, s13, 0
	s_add_i32 s14, vcc_lo, s55
	global_load_lds_dwordx4 v[200:201], off
	v_lshl_add_u64 v[202:203], s[12:13], 0, v[212:213]
	s_mov_b32 m0, s14
	v_lshl_add_u64 v[204:205], s[12:13], 0, v[196:197]
	global_load_lds_dwordx4 v[202:203], off
	s_add_i32 m0, s14, 0x2000
	v_lshl_add_u64 v[206:207], s[96:97], 0, v[192:193]
	global_load_lds_dwordx4 v[204:205], off
	s_mov_b32 m0, s52
	v_lshl_add_u64 v[208:209], s[96:97], 0, v[194:195]
	global_load_lds_dwordx4 v[206:207], off
	s_mov_b32 m0, s31
	s_nop 0
	global_load_lds_dwordx4 v[208:209], off
	s_waitcnt vmcnt(8)
	s_waitcnt lgkmcnt(0)
	s_setprio 1
	s_barrier
; #define PG8_STAGE(bufoff, gbase, voff) do { _Pragma("unroll") for (int _i = 0; _i < 2; ++_i) \
;         __builtin_amdgcn_global_load_lds((const unsigned*)((const char*)(gbase) + (voff)[_i]), (PG8_LAS unsigned*)(lds + (bufoff) + ldsw + _i * 8192), 16, 0, 0); } while (0)
; #define PG8_LDA(dst, b, h) do { _Pragma("unroll") for (int m = 0; m < 4; ++m) _Pragma("unroll") for (int k = 0; k < 2; ++k) dst[m][k] = *(const PG8_LAS bf16x8*)(lds + PG8_SA(b, h) + aoff + m * 2048 + k * 1024); } while (0)
; #define PG8_LDB(dst, b, h) do { _Pragma("unroll") for (int n = 0; n < 2; ++n) _Pragma("unroll") for (int k = 0; k < 2; ++k) dst[n][k] = *(const PG8_LAS bf16x8*)(lds + PG8_SB(b, h) + boff + n * 2048 + k * 1024); } while (0)
; #define PG8_MMA(ai, bj, At, Bt) do { __builtin_amdgcn_s_setprio(1); _Pragma("unroll") for (int m = 0; m < 4; ++m) _Pragma("unroll") for (int n = 0; n < 2; ++n) _Pragma("unroll") for (int k = 0; k < 2; ++k) \
;         acc[ai][bj][m][n] = __builtin_amdgcn_mfma_f32_16x16x32_bf16(Bt[n][k], At[m][k], acc[ai][bj][m][n], 0, 0, 0); __builtin_amdgcn_s_setprio(0); } while (0)
; #define PG8_WAIT_V(n) asm volatile("s_waitcnt vmcnt(" #n ")" ::: "memory")
; #define PG8_WAIT_L(n) asm volatile("s_waitcnt lgkmcnt(" #n ")" ::: "memory")
; #define PG8_BAR __builtin_amdgcn_s_barrier()
; #define PG8_SCHED __builtin_amdgcn_sched_barrier(0)
; template <class Epi, class Sched, bool ALIGN_EPI = false, bool SP2 = false>
; __device__ __forceinline__ void gemm_phase(PG8_LAS unsigned char* lds, const Gemm g, const Sched& S, const Epi& E) {
;     ...
;             PG8_WAIT_V(8); PG8_WAIT_L(0); PG8_BAR; PG8_MMA(1, 0, At, B0); PG8_MMA(1, 1, At, B1); PG8_BAR; PG8_SCHED;
;             PG8_LDB(B0, 1, 0); PG8_LDB(B1, 1, 1); PG8_SCHED; PG8_LDA(At, 1, 0); PG8_STAGE(PG8_SA(0, 1), a2 + hstepA, voffA);
;             PG8_WAIT_V(8); PG8_WAIT_L(0); PG8_BAR; PG8_MMA(0, 0, At, B0); PG8_MMA(0, 1, At, B1); PG8_BAR; PG8_SCHED;
	v_mfma_f32_16x16x32_bf16 v[60:63], v[128:131], v[160:163], v[60:63]
	v_mfma_f32_16x16x32_bf16 v[56:59], v[136:139], v[160:163], v[56:59]
	v_mfma_f32_16x16x32_bf16 v[44:47], v[128:131], v[168:171], v[44:47]
	v_mfma_f32_16x16x32_bf16 v[40:43], v[136:139], v[168:171], v[40:43]
	v_mfma_f32_16x16x32_bf16 v[28:31], v[128:131], v[176:179], v[28:31]
	v_mfma_f32_16x16x32_bf16 v[24:27], v[136:139], v[176:179], v[24:27]
	v_mfma_f32_16x16x32_bf16 v[12:15], v[128:131], v[184:187], v[12:15]
	v_mfma_f32_16x16x32_bf16 v[8:11], v[136:139], v[184:187], v[8:11]
	v_mfma_f32_16x16x32_bf16 v[60:63], v[132:135], v[164:167], v[60:63]
	v_mfma_f32_16x16x32_bf16 v[56:59], v[140:143], v[164:167], v[56:59]
	v_mfma_f32_16x16x32_bf16 v[44:47], v[132:135], v[172:175], v[44:47]
	v_mfma_f32_16x16x32_bf16 v[40:43], v[140:143], v[172:175], v[40:43]
	v_mfma_f32_16x16x32_bf16 v[28:31], v[132:135], v[180:183], v[28:31]
	v_mfma_f32_16x16x32_bf16 v[24:27], v[140:143], v[180:183], v[24:27]
	v_mfma_f32_16x16x32_bf16 v[12:15], v[132:135], v[188:191], v[12:15]
	v_mfma_f32_16x16x32_bf16 v[8:11], v[140:143], v[188:191], v[8:11]
	v_mfma_f32_16x16x32_bf16 v[52:55], v[144:147], v[160:163], v[52:55]
	v_mfma_f32_16x16x32_bf16 v[48:51], v[152:155], v[160:163], v[48:51]
	v_mfma_f32_16x16x32_bf16 v[36:39], v[144:147], v[168:171], v[36:39]
	v_mfma_f32_16x16x32_bf16 v[32:35], v[152:155], v[168:171], v[32:35]
	v_mfma_f32_16x16x32_bf16 v[20:23], v[144:147], v[176:179], v[20:23]
	v_mfma_f32_16x16x32_bf16 v[16:19], v[152:155], v[176:179], v[16:19]
	v_mfma_f32_16x16x32_bf16 v[4:7], v[144:147], v[184:187], v[4:7]
	v_mfma_f32_16x16x32_bf16 v[0:3], v[152:155], v[184:187], v[0:3]
	v_mfma_f32_16x16x32_bf16 v[52:55], v[148:151], v[164:167], v[52:55]
	v_mfma_f32_16x16x32_bf16 v[48:51], v[156:159], v[164:167], v[48:51]
	v_mfma_f32_16x16x32_bf16 v[36:39], v[148:151], v[172:175], v[36:39]
	v_mfma_f32_16x16x32_bf16 v[32:35], v[156:159], v[172:175], v[32:35]
	v_mfma_f32_16x16x32_bf16 v[20:23], v[148:151], v[180:183], v[20:23]
	v_mfma_f32_16x16x32_bf16 v[16:19], v[156:159], v[180:183], v[16:19]
	v_mfma_f32_16x16x32_bf16 v[4:7], v[148:151], v[188:191], v[4:7]
	v_mfma_f32_16x16x32_bf16 v[0:3], v[156:159], v[188:191], v[0:3]
	s_barrier
	s_setprio 0
	s_add_i32 s14, 0, 0x18000
	s_add_i32 s15, 0, 0x1c000
	v_add_u32_e32 v140, s14, v240
	v_add_u32_e32 v156, s15, v240
	ds_read_b128 v[128:131], v140
	ds_read_b128 v[132:135], v140 offset:1024
	ds_read_b128 v[136:139], v140 offset:2048
	ds_read_b128 v[140:143], v140 offset:3072
	ds_read_b128 v[144:147], v156
	ds_read_b128 v[148:151], v156 offset:1024
	ds_read_b128 v[152:155], v156 offset:2048
	ds_read_b128 v[156:159], v156 offset:3072
	s_add_u32 s12, s96, s21
	s_addc_u32 s13, s97, s20
	s_mov_b32 m0, s35
	v_lshl_add_u64 v[210:211], s[12:13], 0, v[192:193]
	ds_read_b128 v[160:163], v243 offset:32768
	ds_read_b128 v[164:167], v243 offset:33792
	ds_read_b128 v[168:171], v243 offset:34816
	ds_read_b128 v[172:175], v243 offset:35840
	ds_read_b128 v[176:179], v243 offset:36864
	ds_read_b128 v[180:183], v243 offset:37888
	ds_read_b128 v[184:187], v243 offset:38912
	ds_read_b128 v[188:191], v243 offset:39936
	global_load_lds_dwordx4 v[210:211], off
	v_lshl_add_u64 v[210:211], s[12:13], 0, v[194:195]
	s_mov_b32 m0, s56
	s_nop 0
	global_load_lds_dwordx4 v[210:211], off
	s_waitcnt vmcnt(8)
	s_waitcnt lgkmcnt(0)
	s_setprio 1
	s_barrier
	v_mfma_f32_16x16x32_bf16 v[124:127], v[128:131], v[160:163], v[124:127]
	v_mfma_f32_16x16x32_bf16 v[120:123], v[136:139], v[160:163], v[120:123]
	v_mfma_f32_16x16x32_bf16 v[108:111], v[128:131], v[168:171], v[108:111]
	v_mfma_f32_16x16x32_bf16 v[104:107], v[136:139], v[168:171], v[104:107]
	v_mfma_f32_16x16x32_bf16 v[92:95], v[128:131], v[176:179], v[92:95]
	v_mfma_f32_16x16x32_bf16 v[88:91], v[136:139], v[176:179], v[88:91]
	v_mfma_f32_16x16x32_bf16 v[76:79], v[128:131], v[184:187], v[76:79]
	v_mfma_f32_16x16x32_bf16 v[72:75], v[136:139], v[184:187], v[72:75]
	v_mfma_f32_16x16x32_bf16 v[124:127], v[132:135], v[164:167], v[124:127]
	v_mfma_f32_16x16x32_bf16 v[120:123], v[140:143], v[164:167], v[120:123]
	v_mfma_f32_16x16x32_bf16 v[108:111], v[132:135], v[172:175], v[108:111]
	v_mfma_f32_16x16x32_bf16 v[104:107], v[140:143], v[172:175], v[104:107]
	v_mfma_f32_16x16x32_bf16 v[92:95], v[132:135], v[180:183], v[92:95]
	v_mfma_f32_16x16x32_bf16 v[88:91], v[140:143], v[180:183], v[88:91]
	v_mfma_f32_16x16x32_bf16 v[76:79], v[132:135], v[188:191], v[76:79]
	v_mfma_f32_16x16x32_bf16 v[72:75], v[140:143], v[188:191], v[72:75]
	v_mfma_f32_16x16x32_bf16 v[116:119], v[144:147], v[160:163], v[116:119]
	v_mfma_f32_16x16x32_bf16 v[112:115], v[152:155], v[160:163], v[112:115]
	v_mfma_f32_16x16x32_bf16 v[100:103], v[144:147], v[168:171], v[100:103]
	v_mfma_f32_16x16x32_bf16 v[96:99], v[152:155], v[168:171], v[96:99]
	v_mfma_f32_16x16x32_bf16 v[84:87], v[144:147], v[176:179], v[84:87]
	v_mfma_f32_16x16x32_bf16 v[80:83], v[152:155], v[176:179], v[80:83]
	v_mfma_f32_16x16x32_bf16 v[68:71], v[144:147], v[184:187], v[68:71]
	v_mfma_f32_16x16x32_bf16 v[64:67], v[152:155], v[184:187], v[64:67]
	v_mfma_f32_16x16x32_bf16 v[116:119], v[148:151], v[164:167], v[116:119]
	v_mfma_f32_16x16x32_bf16 v[112:115], v[156:159], v[164:167], v[112:115]
	v_mfma_f32_16x16x32_bf16 v[100:103], v[148:151], v[172:175], v[100:103]
	v_mfma_f32_16x16x32_bf16 v[96:99], v[156:159], v[172:175], v[96:99]
	v_mfma_f32_16x16x32_bf16 v[84:87], v[148:151], v[180:183], v[84:87]
	v_mfma_f32_16x16x32_bf16 v[80:83], v[156:159], v[180:183], v[80:83]
	v_mfma_f32_16x16x32_bf16 v[68:71], v[148:151], v[188:191], v[68:71]
	v_mfma_f32_16x16x32_bf16 v[64:67], v[156:159], v[188:191], v[64:67]
	s_barrier
; #define PG8_STAGE(bufoff, gbase, voff) do { _Pragma("unroll") for (int _i = 0; _i < 2; ++_i) \
;         __builtin_amdgcn_global_load_lds((const unsigned*)((const char*)(gbase) + (voff)[_i]), (PG8_LAS unsigned*)(lds + (bufoff) + ldsw + _i * 8192), 16, 0, 0); } while (0)
; #define PG8_LDA(dst, b, h) do { _Pragma("unroll") for (int m = 0; m < 4; ++m) _Pragma("unroll") for (int k = 0; k < 2; ++k) dst[m][k] = *(const PG8_LAS bf16x8*)(lds + PG8_SA(b, h) + aoff + m * 2048 + k * 1024); } while (0)
; #define PG8_MMA(ai, bj, At, Bt) do { __builtin_amdgcn_s_setprio(1); _Pragma("unroll") for (int m = 0; m < 4; ++m) _Pragma("unroll") for (int n = 0; n < 2; ++n) _Pragma("unroll") for (int k = 0; k < 2; ++k) \
;         acc[ai][bj][m][n] = __builtin_amdgcn_mfma_f32_16x16x32_bf16(Bt[n][k], At[m][k], acc[ai][bj][m][n], 0, 0, 0); __builtin_amdgcn_s_setprio(0); } while (0)
; #define PG8_WAIT_V(n) asm volatile("s_waitcnt vmcnt(" #n ")" ::: "memory")
; #define PG8_WAIT_L(n) asm volatile("s_waitcnt lgkmcnt(" #n ")" ::: "memory")
; #define PG8_BAR __builtin_amdgcn_s_barrier()
; #define PG8_SCHED __builtin_amdgcn_sched_barrier(0)
; template <class Epi, class Sched, bool ALIGN_EPI = false, bool SP2 = false>
; __device__ __forceinline__ void gemm_phase(PG8_LAS unsigned char* lds, const Gemm g, const Sched& S, const Epi& E) {
;     ...
;             PG8_WAIT_V(8); PG8_WAIT_L(0); PG8_BAR; PG8_MMA(0, 0, At, B0); PG8_MMA(0, 1, At, B1); PG8_BAR; PG8_SCHED;
;             PG8_LDA(At, 1, 1); PG8_STAGE(PG8_SB(1, 0), b3, voffB); PG8_STAGE(PG8_SB(1, 1), b3 + hstep, voffB); PG8_STAGE(PG8_SA(1, 0), a3, voffA);
;             PG8_WAIT_V(8); PG8_WAIT_L(0); PG8_BAR; PG8_MMA(1, 0, At, B0); PG8_MMA(1, 1, At, B1); PG8_BAR; PG8_SCHED;
	s_setprio 0
	s_add_i32 s12, s14, s55
	v_lshl_add_u64 v[198:199], v[198:199], 0, s[22:23]
	s_mov_b32 m0, s12
	ds_read_b128 v[160:163], v243 offset:49152
	ds_read_b128 v[164:167], v243 offset:50176
	ds_read_b128 v[168:171], v243 offset:51200
	ds_read_b128 v[172:175], v243 offset:52224
	ds_read_b128 v[176:179], v243 offset:53248
	ds_read_b128 v[180:183], v243 offset:54272
	ds_read_b128 v[184:187], v243 offset:55296
	ds_read_b128 v[188:191], v243 offset:56320
	global_load_lds_dwordx4 v[198:199], off
	v_lshl_add_u64 v[198:199], v[200:201], 0, s[22:23]
	s_add_i32 m0, s12, 0x2000
	s_add_i32 s12, s15, s55
	global_load_lds_dwordx4 v[198:199], off
	v_lshl_add_u64 v[198:199], v[202:203], 0, s[22:23]
	s_mov_b32 m0, s12
	s_nop 0
	global_load_lds_dwordx4 v[198:199], off
	v_lshl_add_u64 v[198:199], v[204:205], 0, s[22:23]
	s_add_i32 m0, s12, 0x2000
	s_nop 0
	global_load_lds_dwordx4 v[198:199], off
	v_lshl_add_u64 v[198:199], v[206:207], 0, s[22:23]
	s_mov_b32 m0, s17
	s_nop 0
	global_load_lds_dwordx4 v[198:199], off
	v_lshl_add_u64 v[198:199], v[208:209], 0, s[22:23]
	s_mov_b32 m0, s27
	s_nop 0
	global_load_lds_dwordx4 v[198:199], off
	s_waitcnt vmcnt(8)
	s_waitcnt lgkmcnt(0)
	s_setprio 1
	s_barrier
	v_mfma_f32_16x16x32_bf16 v[60:63], v[128:131], v[160:163], v[60:63]
	v_mfma_f32_16x16x32_bf16 v[56:59], v[136:139], v[160:163], v[56:59]
	v_mfma_f32_16x16x32_bf16 v[44:47], v[128:131], v[168:171], v[44:47]
	v_mfma_f32_16x16x32_bf16 v[40:43], v[136:139], v[168:171], v[40:43]
	v_mfma_f32_16x16x32_bf16 v[28:31], v[128:131], v[176:179], v[28:31]
	v_mfma_f32_16x16x32_bf16 v[24:27], v[136:139], v[176:179], v[24:27]
	v_mfma_f32_16x16x32_bf16 v[12:15], v[128:131], v[184:187], v[12:15]
	v_mfma_f32_16x16x32_bf16 v[8:11], v[136:139], v[184:187], v[8:11]
	v_mfma_f32_16x16x32_bf16 v[60:63], v[132:135], v[164:167], v[60:63]
	v_mfma_f32_16x16x32_bf16 v[56:59], v[140:143], v[164:167], v[56:59]
	v_mfma_f32_16x16x32_bf16 v[44:47], v[132:135], v[172:175], v[44:47]
	v_mfma_f32_16x16x32_bf16 v[40:43], v[140:143], v[172:175], v[40:43]
	v_mfma_f32_16x16x32_bf16 v[28:31], v[132:135], v[180:183], v[28:31]
	v_mfma_f32_16x16x32_bf16 v[24:27], v[140:143], v[180:183], v[24:27]
	v_mfma_f32_16x16x32_bf16 v[12:15], v[132:135], v[188:191], v[12:15]
	v_mfma_f32_16x16x32_bf16 v[8:11], v[140:143], v[188:191], v[8:11]
	v_mfma_f32_16x16x32_bf16 v[52:55], v[144:147], v[160:163], v[52:55]
	v_mfma_f32_16x16x32_bf16 v[48:51], v[152:155], v[160:163], v[48:51]
	v_mfma_f32_16x16x32_bf16 v[36:39], v[144:147], v[168:171], v[36:39]
	v_mfma_f32_16x16x32_bf16 v[32:35], v[152:155], v[168:171], v[32:35]
	v_mfma_f32_16x16x32_bf16 v[20:23], v[144:147], v[176:179], v[20:23]
	v_mfma_f32_16x16x32_bf16 v[16:19], v[152:155], v[176:179], v[16:19]
	v_mfma_f32_16x16x32_bf16 v[4:7], v[144:147], v[184:187], v[4:7]
	v_mfma_f32_16x16x32_bf16 v[0:3], v[152:155], v[184:187], v[0:3]
	v_mfma_f32_16x16x32_bf16 v[52:55], v[148:151], v[164:167], v[52:55]
	v_mfma_f32_16x16x32_bf16 v[48:51], v[156:159], v[164:167], v[48:51]
	v_mfma_f32_16x16x32_bf16 v[36:39], v[148:151], v[172:175], v[36:39]
	v_mfma_f32_16x16x32_bf16 v[32:35], v[156:159], v[172:175], v[32:35]
	v_mfma_f32_16x16x32_bf16 v[20:23], v[148:151], v[180:183], v[20:23]
	v_mfma_f32_16x16x32_bf16 v[16:19], v[156:159], v[180:183], v[16:19]
	v_mfma_f32_16x16x32_bf16 v[4:7], v[148:151], v[188:191], v[4:7]
	v_mfma_f32_16x16x32_bf16 v[0:3], v[156:159], v[188:191], v[0:3]
	s_barrier
	s_setprio 0
	s_add_i32 s12, s36, 2
	s_add_u32 s40, s40, 0x100
	s_addc_u32 s41, s41, 0
	s_cmp_ge_u32 s36, s16
	s_mov_b32 s36, s12
	s_cbranch_scc1 .LBB0_191

; #define PG8_STAGE(bufoff, gbase, voff) do { _Pragma("unroll") for (int _i = 0; _i < 2; ++_i) \
;         __builtin_amdgcn_global_load_lds((const unsigned*)((const char*)(gbase) + (voff)[_i]), (PG8_LAS unsigned*)(lds + (bufoff) + ldsw + _i * 8192), 16, 0, 0); } while (0)
; #define PG8_LDA(dst, b, h) do { _Pragma("unroll") for (int m = 0; m < 4; ++m) _Pragma("unroll") for (int k = 0; k < 2; ++k) dst[m][k] = *(const PG8_LAS bf16x8*)(lds + PG8_SA(b, h) + aoff + m * 2048 + k * 1024); } while (0)
; #define PG8_LDB(dst, b, h) do { _Pragma("unroll") for (int n = 0; n < 2; ++n) _Pragma("unroll") for (int k = 0; k < 2; ++k) dst[n][k] = *(const PG8_LAS bf16x8*)(lds + PG8_SB(b, h) + boff + n * 2048 + k * 1024); } while (0)
; #define PG8_MMA(ai, bj, At, Bt) do { __builtin_amdgcn_s_setprio(1); _Pragma("unroll") for (int m = 0; m < 4; ++m) _Pragma("unroll") for (int n = 0; n < 2; ++n) _Pragma("unroll") for (int k = 0; k < 2; ++k) \
;         acc[ai][bj][m][n] = __builtin_amdgcn_mfma_f32_16x16x32_bf16(Bt[n][k], At[m][k], acc[ai][bj][m][n], 0, 0, 0); __builtin_amdgcn_s_setprio(0); } while (0)
; #define PG8_BAR __builtin_amdgcn_s_barrier()
; template <class Epi, class Sched, bool ALIGN_EPI = false, bool SP2 = false>
; __device__ __forceinline__ void gemm_phase(PG8_LAS unsigned char* lds, const Gemm g, const Sched& S, const Epi& E) {
;     ...
;             const bool last = (t == nt - 2);
;             const char* a1 = cA + (g.gstrA ? (size_t)(t >> 2) * g.gstrA + (size_t)(t & 3) * kstep : (size_t)t * kstep) + kstep;
;             const char* a2 = last ? nA : cA + (g.gstrA ? (size_t)((t + 2) >> 2) * g.gstrA + (size_t)((t + 2) & 3) * kstep : (size_t)(t + 2) * kstep); const char* b2 = last ? nB : cB + (size_t)(t + 2) * kstep;
;             const char* a3 = a2 + kstep; const char* b3 = b2 + kstep;
;             if (last && has_next) S.a_ready(nxt);
;             if constexpr (Epi::HAS_PREFETCH) { if (t == nt - 4) E.prefetch(cur, tid, wid); }
;             if constexpr (SP2) {
;             PG8_LDB(B0, 0, 0); PG8_LDB(B1, 0, 1); PG8_SCHED; PG8_LDA(At, 0, 0); PG8_STAGE(PG8_SA(1, 1), a1 + hstepA, voffA);
;             PG8_WAIT_V(8); PG8_WAIT_L(0); PG8_BAR; PG8_MMA(0, 0, At, B0); PG8_MMA(0, 1, At, B1); PG8_BAR; PG8_SCHED;
;             PG8_LDA(At, 0, 1); PG8_STAGE(PG8_SB(0, 0), b2, voffB); PG8_STAGE(PG8_SB(0, 1), b2 + hstep, voffB); PG8_STAGE(PG8_SA(0, 0), a2, voffA);
.LBB0_369:
	s_add_u32 s14, s68, 0xfffc0080
	s_addc_u32 s15, s69, -1
	s_add_i32 s59, 0, 0x10000
	s_cmp_eq_u32 s52, 12
	s_cselect_b32 s15, s24, s15
	s_cselect_b32 s14, s26, s14
	s_cselect_b32 s41, s30, s37
	s_cselect_b32 s40, s34, s36
	s_add_i32 s61, 0, 0x14000
	v_add_u32_e32 v162, s59, v139
	v_add_u32_e32 v178, s61, v139
	ds_read_b128 v[150:153], v162
	ds_read_b128 v[154:157], v162 offset:1024
	ds_read_b128 v[158:161], v162 offset:2048
	ds_read_b128 v[162:165], v162 offset:3072
	ds_read_b128 v[166:169], v178
	ds_read_b128 v[170:173], v178 offset:1024
	ds_read_b128 v[174:177], v178 offset:2048
	ds_read_b128 v[178:181], v178 offset:3072
	v_lshl_add_u64 v[210:211], s[68:69], 0, v[134:135]
	s_add_i32 m0, s17, 0xc000
	ds_read_b128 v[182:185], v149
	ds_read_b128 v[186:189], v149 offset:1024
	ds_read_b128 v[190:193], v149 offset:2048
	ds_read_b128 v[194:197], v149 offset:3072
	ds_read_b128 v[198:201], v149 offset:4096
	ds_read_b128 v[202:205], v149 offset:5120
	ds_read_b128 v[206:209], v149 offset:6144
	ds_read_b128 v[214:217], v149 offset:7168
	global_load_lds_dwordx4 v[210:211], off
	v_lshl_add_u64 v[210:211], s[68:69], 0, v[136:137]
	s_add_i32 m0, s17, 0xe000
	s_nop 0
	global_load_lds_dwordx4 v[210:211], off
	s_waitcnt vmcnt(8)
	s_waitcnt lgkmcnt(0)
	s_setprio 1
	s_barrier
	v_mfma_f32_16x16x32_bf16 v[124:127], v[150:153], v[182:185], v[124:127]
	v_mfma_f32_16x16x32_bf16 v[116:119], v[158:161], v[182:185], v[116:119]
	v_mfma_f32_16x16x32_bf16 v[108:111], v[150:153], v[190:193], v[108:111]
	v_mfma_f32_16x16x32_bf16 v[100:103], v[158:161], v[190:193], v[100:103]
	v_mfma_f32_16x16x32_bf16 v[92:95], v[150:153], v[198:201], v[92:95]
	v_mfma_f32_16x16x32_bf16 v[84:87], v[158:161], v[198:201], v[84:87]
	v_mfma_f32_16x16x32_bf16 v[76:79], v[150:153], v[206:209], v[76:79]
	v_mfma_f32_16x16x32_bf16 v[68:71], v[158:161], v[206:209], v[68:71]
	v_mfma_f32_16x16x32_bf16 v[124:127], v[154:157], v[186:189], v[124:127]
	v_mfma_f32_16x16x32_bf16 v[116:119], v[162:165], v[186:189], v[116:119]
	v_mfma_f32_16x16x32_bf16 v[108:111], v[154:157], v[194:197], v[108:111]
	v_mfma_f32_16x16x32_bf16 v[100:103], v[162:165], v[194:197], v[100:103]
	v_mfma_f32_16x16x32_bf16 v[92:95], v[154:157], v[202:205], v[92:95]
	v_mfma_f32_16x16x32_bf16 v[84:87], v[162:165], v[202:205], v[84:87]
	v_mfma_f32_16x16x32_bf16 v[76:79], v[154:157], v[214:217], v[76:79]
	v_mfma_f32_16x16x32_bf16 v[68:71], v[162:165], v[214:217], v[68:71]
	v_mfma_f32_16x16x32_bf16 v[120:123], v[166:169], v[182:185], v[120:123]
	v_mfma_f32_16x16x32_bf16 v[112:115], v[174:177], v[182:185], v[112:115]
	v_mfma_f32_16x16x32_bf16 v[104:107], v[166:169], v[190:193], v[104:107]
	v_mfma_f32_16x16x32_bf16 v[96:99], v[174:177], v[190:193], v[96:99]
	v_mfma_f32_16x16x32_bf16 v[88:91], v[166:169], v[198:201], v[88:91]
	v_mfma_f32_16x16x32_bf16 v[80:83], v[174:177], v[198:201], v[80:83]
	v_mfma_f32_16x16x32_bf16 v[72:75], v[166:169], v[206:209], v[72:75]
	v_mfma_f32_16x16x32_bf16 v[64:67], v[174:177], v[206:209], v[64:67]
	v_mfma_f32_16x16x32_bf16 v[120:123], v[170:173], v[186:189], v[120:123]
	v_mfma_f32_16x16x32_bf16 v[112:115], v[178:181], v[186:189], v[112:115]
	v_mfma_f32_16x16x32_bf16 v[104:107], v[170:173], v[194:197], v[104:107]
	v_mfma_f32_16x16x32_bf16 v[96:99], v[178:181], v[194:197], v[96:99]
	v_mfma_f32_16x16x32_bf16 v[88:91], v[170:173], v[202:205], v[88:91]
	v_mfma_f32_16x16x32_bf16 v[80:83], v[178:181], v[202:205], v[80:83]
	v_mfma_f32_16x16x32_bf16 v[72:75], v[170:173], v[214:217], v[72:75]
	v_mfma_f32_16x16x32_bf16 v[64:67], v[178:181], v[214:217], v[64:67]
	s_barrier
	s_setprio 0
	s_add_i32 s59, s59, s2
	v_lshl_add_u64 v[210:211], s[40:41], 0, v[212:213]
	s_mov_b32 m0, s59
	ds_read_b128 v[182:185], v149 offset:16384
	ds_read_b128 v[186:189], v149 offset:17408
	ds_read_b128 v[190:193], v149 offset:18432
	ds_read_b128 v[194:197], v149 offset:19456
	ds_read_b128 v[198:201], v149 offset:20480
	ds_read_b128 v[202:205], v149 offset:21504
	ds_read_b128 v[206:209], v149 offset:22528
	ds_read_b128 v[214:217], v149 offset:23552
	global_load_lds_dwordx4 v[210:211], off
	s_add_i32 m0, s59, 0x2000
	s_add_u32 s70, s40, 0x40000
	v_lshl_add_u64 v[218:219], s[40:41], 0, v[128:129]
	s_addc_u32 s71, s41, 0
	s_add_i32 s59, s61, s2
	global_load_lds_dwordx4 v[218:219], off
	v_lshl_add_u64 v[220:221], s[70:71], 0, v[212:213]
	s_mov_b32 m0, s59
	v_lshl_add_u64 v[222:223], s[14:15], 0, v[130:131]
	global_load_lds_dwordx4 v[220:221], off
	v_lshl_add_u64 v[220:221], s[70:71], 0, v[128:129]
	s_add_i32 m0, s59, 0x2000
	s_nop 0
	global_load_lds_dwordx4 v[220:221], off
	v_lshl_add_u64 v[220:221], s[14:15], 0, v[132:133]
	s_mov_b32 m0, s17
	s_nop 0
	global_load_lds_dwordx4 v[220:221], off
	s_mov_b32 m0, s18
	s_nop 0
	global_load_lds_dwordx4 v[222:223], off
	s_waitcnt vmcnt(8)
	s_waitcnt lgkmcnt(0)
	s_setprio 1
	s_barrier
; #define PG8_STAGE(bufoff, gbase, voff) do { _Pragma("unroll") for (int _i = 0; _i < 2; ++_i) \
;         __builtin_amdgcn_global_load_lds((const unsigned*)((const char*)(gbase) + (voff)[_i]), (PG8_LAS unsigned*)(lds + (bufoff) + ldsw + _i * 8192), 16, 0, 0); } while (0)
; #define PG8_LDA(dst, b, h) do { _Pragma("unroll") for (int m = 0; m < 4; ++m) _Pragma("unroll") for (int k = 0; k < 2; ++k) dst[m][k] = *(const PG8_LAS bf16x8*)(lds + PG8_SA(b, h) + aoff + m * 2048 + k * 1024); } while (0)
; #define PG8_LDB(dst, b, h) do { _Pragma("unroll") for (int n = 0; n < 2; ++n) _Pragma("unroll") for (int k = 0; k < 2; ++k) dst[n][k] = *(const PG8_LAS bf16x8*)(lds + PG8_SB(b, h) + boff + n * 2048 + k * 1024); } while (0)
; #define PG8_MMA(ai, bj, At, Bt) do { __builtin_amdgcn_s_setprio(1); _Pragma("unroll") for (int m = 0; m < 4; ++m) _Pragma("unroll") for (int n = 0; n < 2; ++n) _Pragma("unroll") for (int k = 0; k < 2; ++k) \
;         acc[ai][bj][m][n] = __builtin_amdgcn_mfma_f32_16x16x32_bf16(Bt[n][k], At[m][k], acc[ai][bj][m][n], 0, 0, 0); __builtin_amdgcn_s_setprio(0); } while (0)
; #define PG8_WAIT_V(n) asm volatile("s_waitcnt vmcnt(" #n ")" ::: "memory")
; #define PG8_WAIT_L(n) asm volatile("s_waitcnt lgkmcnt(" #n ")" ::: "memory")
; #define PG8_BAR __builtin_amdgcn_s_barrier()
; #define PG8_SCHED __builtin_amdgcn_sched_barrier(0)
; template <class Epi, class Sched, bool ALIGN_EPI = false, bool SP2 = false>
; __device__ __forceinline__ void gemm_phase(PG8_LAS unsigned char* lds, const Gemm g, const Sched& S, const Epi& E) {
;     ...
;             PG8_WAIT_V(8); PG8_WAIT_L(0); PG8_BAR; PG8_MMA(1, 0, At, B0); PG8_MMA(1, 1, At, B1); PG8_BAR; PG8_SCHED;
;             PG8_LDB(B0, 1, 0); PG8_LDB(B1, 1, 1); PG8_SCHED; PG8_LDA(At, 1, 0); PG8_STAGE(PG8_SA(0, 1), a2 + hstepA, voffA);
;             PG8_WAIT_V(8); PG8_WAIT_L(0); PG8_BAR; PG8_MMA(0, 0, At, B0); PG8_MMA(0, 1, At, B1); PG8_BAR; PG8_SCHED;
	v_mfma_f32_16x16x32_bf16 v[60:63], v[150:153], v[182:185], v[60:63]
	v_mfma_f32_16x16x32_bf16 v[52:55], v[158:161], v[182:185], v[52:55]
	v_mfma_f32_16x16x32_bf16 v[44:47], v[150:153], v[190:193], v[44:47]
	v_mfma_f32_16x16x32_bf16 v[36:39], v[158:161], v[190:193], v[36:39]
	v_mfma_f32_16x16x32_bf16 v[28:31], v[150:153], v[198:201], v[28:31]
	v_mfma_f32_16x16x32_bf16 v[20:23], v[158:161], v[198:201], v[20:23]
	v_mfma_f32_16x16x32_bf16 v[12:15], v[150:153], v[206:209], v[12:15]
	v_mfma_f32_16x16x32_bf16 v[4:7], v[158:161], v[206:209], v[4:7]
	v_mfma_f32_16x16x32_bf16 v[60:63], v[154:157], v[186:189], v[60:63]
	v_mfma_f32_16x16x32_bf16 v[52:55], v[162:165], v[186:189], v[52:55]
	v_mfma_f32_16x16x32_bf16 v[44:47], v[154:157], v[194:197], v[44:47]
	v_mfma_f32_16x16x32_bf16 v[36:39], v[162:165], v[194:197], v[36:39]
	v_mfma_f32_16x16x32_bf16 v[28:31], v[154:157], v[202:205], v[28:31]
	v_mfma_f32_16x16x32_bf16 v[20:23], v[162:165], v[202:205], v[20:23]
	v_mfma_f32_16x16x32_bf16 v[12:15], v[154:157], v[214:217], v[12:15]
	v_mfma_f32_16x16x32_bf16 v[4:7], v[162:165], v[214:217], v[4:7]
	v_mfma_f32_16x16x32_bf16 v[56:59], v[166:169], v[182:185], v[56:59]
	v_mfma_f32_16x16x32_bf16 v[48:51], v[174:177], v[182:185], v[48:51]
	v_mfma_f32_16x16x32_bf16 v[40:43], v[166:169], v[190:193], v[40:43]
	v_mfma_f32_16x16x32_bf16 v[32:35], v[174:177], v[190:193], v[32:35]
	v_mfma_f32_16x16x32_bf16 v[24:27], v[166:169], v[198:201], v[24:27]
	v_mfma_f32_16x16x32_bf16 v[16:19], v[174:177], v[198:201], v[16:19]
	v_mfma_f32_16x16x32_bf16 v[8:11], v[166:169], v[206:209], v[8:11]
	v_mfma_f32_16x16x32_bf16 v[0:3], v[174:177], v[206:209], v[0:3]
	v_mfma_f32_16x16x32_bf16 v[56:59], v[170:173], v[186:189], v[56:59]
	v_mfma_f32_16x16x32_bf16 v[48:51], v[178:181], v[186:189], v[48:51]
	v_mfma_f32_16x16x32_bf16 v[40:43], v[170:173], v[194:197], v[40:43]
	v_mfma_f32_16x16x32_bf16 v[32:35], v[178:181], v[194:197], v[32:35]
	v_mfma_f32_16x16x32_bf16 v[24:27], v[170:173], v[202:205], v[24:27]
	v_mfma_f32_16x16x32_bf16 v[16:19], v[178:181], v[202:205], v[16:19]
	v_mfma_f32_16x16x32_bf16 v[8:11], v[170:173], v[214:217], v[8:11]
	v_mfma_f32_16x16x32_bf16 v[0:3], v[178:181], v[214:217], v[0:3]
	s_barrier
	s_setprio 0
	s_add_i32 s59, 0, 0x18000
	s_add_i32 s61, 0, 0x1c000
	v_add_u32_e32 v162, s59, v139
	v_add_u32_e32 v178, s61, v139
	ds_read_b128 v[150:153], v162
	ds_read_b128 v[154:157], v162 offset:1024
	ds_read_b128 v[158:161], v162 offset:2048
	ds_read_b128 v[162:165], v162 offset:3072
	ds_read_b128 v[166:169], v178
	ds_read_b128 v[170:173], v178 offset:1024
	ds_read_b128 v[174:177], v178 offset:2048
	ds_read_b128 v[178:181], v178 offset:3072
	s_add_u32 s14, s14, 0x40000
	s_addc_u32 s15, s15, 0
	s_mov_b32 m0, s20
	v_lshl_add_u64 v[224:225], s[14:15], 0, v[132:133]
	ds_read_b128 v[182:185], v149 offset:32768
	ds_read_b128 v[186:189], v149 offset:33792
	ds_read_b128 v[190:193], v149 offset:34816
	ds_read_b128 v[194:197], v149 offset:35840
	ds_read_b128 v[198:201], v149 offset:36864
	ds_read_b128 v[202:205], v149 offset:37888
	ds_read_b128 v[206:209], v149 offset:38912
	ds_read_b128 v[214:217], v149 offset:39936
	global_load_lds_dwordx4 v[224:225], off
	v_lshl_add_u64 v[224:225], s[14:15], 0, v[130:131]
	s_mov_b32 m0, s21
	s_nop 0
	global_load_lds_dwordx4 v[224:225], off
	s_waitcnt vmcnt(8)
	s_waitcnt lgkmcnt(0)
	s_setprio 1
	s_barrier
	v_mfma_f32_16x16x32_bf16 v[124:127], v[150:153], v[182:185], v[124:127]
	v_mfma_f32_16x16x32_bf16 v[116:119], v[158:161], v[182:185], v[116:119]
	v_mfma_f32_16x16x32_bf16 v[108:111], v[150:153], v[190:193], v[108:111]
	v_mfma_f32_16x16x32_bf16 v[100:103], v[158:161], v[190:193], v[100:103]
	v_mfma_f32_16x16x32_bf16 v[92:95], v[150:153], v[198:201], v[92:95]
	v_mfma_f32_16x16x32_bf16 v[84:87], v[158:161], v[198:201], v[84:87]
	v_mfma_f32_16x16x32_bf16 v[76:79], v[150:153], v[206:209], v[76:79]
	v_mfma_f32_16x16x32_bf16 v[68:71], v[158:161], v[206:209], v[68:71]
	v_mfma_f32_16x16x32_bf16 v[124:127], v[154:157], v[186:189], v[124:127]
	v_mfma_f32_16x16x32_bf16 v[116:119], v[162:165], v[186:189], v[116:119]
	v_mfma_f32_16x16x32_bf16 v[108:111], v[154:157], v[194:197], v[108:111]
	v_mfma_f32_16x16x32_bf16 v[100:103], v[162:165], v[194:197], v[100:103]
	v_mfma_f32_16x16x32_bf16 v[92:95], v[154:157], v[202:205], v[92:95]
	v_mfma_f32_16x16x32_bf16 v[84:87], v[162:165], v[202:205], v[84:87]
	v_mfma_f32_16x16x32_bf16 v[76:79], v[154:157], v[214:217], v[76:79]
	v_mfma_f32_16x16x32_bf16 v[68:71], v[162:165], v[214:217], v[68:71]
	v_mfma_f32_16x16x32_bf16 v[120:123], v[166:169], v[182:185], v[120:123]
	v_mfma_f32_16x16x32_bf16 v[112:115], v[174:177], v[182:185], v[112:115]
	v_mfma_f32_16x16x32_bf16 v[104:107], v[166:169], v[190:193], v[104:107]
	v_mfma_f32_16x16x32_bf16 v[96:99], v[174:177], v[190:193], v[96:99]
	v_mfma_f32_16x16x32_bf16 v[88:91], v[166:169], v[198:201], v[88:91]
	v_mfma_f32_16x16x32_bf16 v[80:83], v[174:177], v[198:201], v[80:83]
	v_mfma_f32_16x16x32_bf16 v[72:75], v[166:169], v[206:209], v[72:75]
	v_mfma_f32_16x16x32_bf16 v[64:67], v[174:177], v[206:209], v[64:67]
	v_mfma_f32_16x16x32_bf16 v[120:123], v[170:173], v[186:189], v[120:123]
	v_mfma_f32_16x16x32_bf16 v[112:115], v[178:181], v[186:189], v[112:115]
	v_mfma_f32_16x16x32_bf16 v[104:107], v[170:173], v[194:197], v[104:107]
	v_mfma_f32_16x16x32_bf16 v[96:99], v[178:181], v[194:197], v[96:99]
	v_mfma_f32_16x16x32_bf16 v[88:91], v[170:173], v[202:205], v[88:91]
	v_mfma_f32_16x16x32_bf16 v[80:83], v[178:181], v[202:205], v[80:83]
	v_mfma_f32_16x16x32_bf16 v[72:75], v[170:173], v[214:217], v[72:75]
	v_mfma_f32_16x16x32_bf16 v[64:67], v[178:181], v[214:217], v[64:67]
	s_barrier
; #define PG8_STAGE(bufoff, gbase, voff) do { _Pragma("unroll") for (int _i = 0; _i < 2; ++_i) \
;         __builtin_amdgcn_global_load_lds((const unsigned*)((const char*)(gbase) + (voff)[_i]), (PG8_LAS unsigned*)(lds + (bufoff) + ldsw + _i * 8192), 16, 0, 0); } while (0)
; #define PG8_LDA(dst, b, h) do { _Pragma("unroll") for (int m = 0; m < 4; ++m) _Pragma("unroll") for (int k = 0; k < 2; ++k) dst[m][k] = *(const PG8_LAS bf16x8*)(lds + PG8_SA(b, h) + aoff + m * 2048 + k * 1024); } while (0)
; #define PG8_MMA(ai, bj, At, Bt) do { __builtin_amdgcn_s_setprio(1); _Pragma("unroll") for (int m = 0; m < 4; ++m) _Pragma("unroll") for (int n = 0; n < 2; ++n) _Pragma("unroll") for (int k = 0; k < 2; ++k) \
;         acc[ai][bj][m][n] = __builtin_amdgcn_mfma_f32_16x16x32_bf16(Bt[n][k], At[m][k], acc[ai][bj][m][n], 0, 0, 0); __builtin_amdgcn_s_setprio(0); } while (0)
; #define PG8_WAIT_V(n) asm volatile("s_waitcnt vmcnt(" #n ")" ::: "memory")
; #define PG8_WAIT_L(n) asm volatile("s_waitcnt lgkmcnt(" #n ")" ::: "memory")
; #define PG8_BAR __builtin_amdgcn_s_barrier()
; #define PG8_SCHED __builtin_amdgcn_sched_barrier(0)
; template <class Epi, class Sched, bool ALIGN_EPI = false, bool SP2 = false>
; __device__ __forceinline__ void gemm_phase(PG8_LAS unsigned char* lds, const Gemm g, const Sched& S, const Epi& E) {
;     ...
;             PG8_LDA(At, 1, 1); PG8_STAGE(PG8_SB(1, 0), b3, voffB); PG8_STAGE(PG8_SB(1, 1), b3 + hstep, voffB); PG8_STAGE(PG8_SA(1, 0), a3, voffA);
;             PG8_WAIT_V(8); PG8_WAIT_L(0); PG8_BAR; PG8_MMA(1, 0, At, B0); PG8_MMA(1, 1, At, B1); PG8_BAR; PG8_SCHED;
;     ...
;         if constexpr (ALIGN_EPI) { if (wr == 0) PG8_BAR; }
	s_setprio 0
	s_add_i32 s14, s59, s2
	v_lshl_add_u64 v[210:211], v[210:211], 0, s[22:23]
	s_mov_b32 m0, s14
	ds_read_b128 v[182:185], v149 offset:49152
	ds_read_b128 v[186:189], v149 offset:50176
	ds_read_b128 v[190:193], v149 offset:51200
	ds_read_b128 v[194:197], v149 offset:52224
	ds_read_b128 v[198:201], v149 offset:53248
	ds_read_b128 v[202:205], v149 offset:54272
	ds_read_b128 v[206:209], v149 offset:55296
	ds_read_b128 v[214:217], v149 offset:56320
	global_load_lds_dwordx4 v[210:211], off
	s_add_i32 m0, s14, 0x2000
	s_add_u32 s14, s40, 0x40080
	v_lshl_add_u64 v[210:211], v[218:219], 0, s[22:23]
	s_addc_u32 s15, s41, 0
	s_add_i32 s40, s61, s2
	global_load_lds_dwordx4 v[210:211], off
	v_lshl_add_u64 v[210:211], s[14:15], 0, v[212:213]
	s_mov_b32 m0, s40
	s_nop 0
	global_load_lds_dwordx4 v[210:211], off
	v_lshl_add_u64 v[210:211], s[14:15], 0, v[128:129]
	s_add_i32 m0, s40, 0x2000
	s_nop 0
	global_load_lds_dwordx4 v[210:211], off
	v_lshl_add_u64 v[210:211], v[220:221], 0, s[22:23]
	s_mov_b32 m0, s25
	s_nop 0
	global_load_lds_dwordx4 v[210:211], off
	v_lshl_add_u64 v[210:211], v[222:223], 0, s[22:23]
	s_mov_b32 m0, s27
	s_nop 0
	global_load_lds_dwordx4 v[210:211], off
	s_waitcnt vmcnt(8)
	s_waitcnt lgkmcnt(0)
	s_setprio 1
	s_barrier
	v_mfma_f32_16x16x32_bf16 v[60:63], v[150:153], v[182:185], v[60:63]
	v_mfma_f32_16x16x32_bf16 v[52:55], v[158:161], v[182:185], v[52:55]
	v_mfma_f32_16x16x32_bf16 v[44:47], v[150:153], v[190:193], v[44:47]
	v_mfma_f32_16x16x32_bf16 v[36:39], v[158:161], v[190:193], v[36:39]
	v_mfma_f32_16x16x32_bf16 v[28:31], v[150:153], v[198:201], v[28:31]
	v_mfma_f32_16x16x32_bf16 v[20:23], v[158:161], v[198:201], v[20:23]
	v_mfma_f32_16x16x32_bf16 v[12:15], v[150:153], v[206:209], v[12:15]
	v_mfma_f32_16x16x32_bf16 v[4:7], v[158:161], v[206:209], v[4:7]
	v_mfma_f32_16x16x32_bf16 v[60:63], v[154:157], v[186:189], v[60:63]
	v_mfma_f32_16x16x32_bf16 v[52:55], v[162:165], v[186:189], v[52:55]
	v_mfma_f32_16x16x32_bf16 v[44:47], v[154:157], v[194:197], v[44:47]
	v_mfma_f32_16x16x32_bf16 v[36:39], v[162:165], v[194:197], v[36:39]
	v_mfma_f32_16x16x32_bf16 v[28:31], v[154:157], v[202:205], v[28:31]
	v_mfma_f32_16x16x32_bf16 v[20:23], v[162:165], v[202:205], v[20:23]
	v_mfma_f32_16x16x32_bf16 v[12:15], v[154:157], v[214:217], v[12:15]
	v_mfma_f32_16x16x32_bf16 v[4:7], v[162:165], v[214:217], v[4:7]
	v_mfma_f32_16x16x32_bf16 v[56:59], v[166:169], v[182:185], v[56:59]
	v_mfma_f32_16x16x32_bf16 v[48:51], v[174:177], v[182:185], v[48:51]
	v_mfma_f32_16x16x32_bf16 v[40:43], v[166:169], v[190:193], v[40:43]
	v_mfma_f32_16x16x32_bf16 v[32:35], v[174:177], v[190:193], v[32:35]
	v_mfma_f32_16x16x32_bf16 v[24:27], v[166:169], v[198:201], v[24:27]
	v_mfma_f32_16x16x32_bf16 v[16:19], v[174:177], v[198:201], v[16:19]
	v_mfma_f32_16x16x32_bf16 v[8:11], v[166:169], v[206:209], v[8:11]
	v_mfma_f32_16x16x32_bf16 v[0:3], v[174:177], v[206:209], v[0:3]
	v_mfma_f32_16x16x32_bf16 v[56:59], v[170:173], v[186:189], v[56:59]
	v_mfma_f32_16x16x32_bf16 v[48:51], v[178:181], v[186:189], v[48:51]
	v_mfma_f32_16x16x32_bf16 v[40:43], v[170:173], v[194:197], v[40:43]
	v_mfma_f32_16x16x32_bf16 v[32:35], v[178:181], v[194:197], v[32:35]
	v_mfma_f32_16x16x32_bf16 v[24:27], v[170:173], v[202:205], v[24:27]
	v_mfma_f32_16x16x32_bf16 v[16:19], v[178:181], v[202:205], v[16:19]
	v_mfma_f32_16x16x32_bf16 v[8:11], v[170:173], v[214:217], v[8:11]
	v_mfma_f32_16x16x32_bf16 v[0:3], v[178:181], v[214:217], v[0:3]
	s_barrier
	s_setprio 0
	s_add_i32 s52, s52, 2
	s_add_u32 s68, s68, 0x100
	s_addc_u32 s69, s69, 0
	s_add_u32 s36, s36, 0x100
	s_addc_u32 s37, s37, 0
	s_cmp_gt_u32 s52, 13
	s_cbranch_scc0 .LBB0_369
	s_and_b64 vcc, exec, s[56:57]
	s_cbranch_vccz .LBB0_372
	s_barrier
